# split-K tail rounds for G9 (layer0, 4-way) and G8 (layer0 4-way, layer1 2-way): partials via write-through stores, counter + fences, deterministic fixed-order combine; wave-group barrier stagger re-al
# baseline (speedup 1.0000x reference)
;     DI bool next(int i, Unit& u) const { const int L = (i0 + i) * G + c - start; if (L >= 144) return false; const int bt = L >> 2; u.pm = L & 3; u.pn = (bt / 9) * 16 + (bt % 9); u.kob = 256 * u.pm; return true; }
;     DI const float* inp(int i) const { return as_global(P.in[i]); }
; #define REP(k) for (int rep_ = 0, nrep_ = F.nrep((DUPMASK >> (k)) & 1); rep_ < nrep_; ++rep_)
; template <class Epi, class SchedT>
; DI void gemm_phase(LAS unsigned char* lds, const Gemm g, const SchedT& S, const Epi& E) {
;     ...
;     Unit cur, nxt; int ui = 0;
;     if (!S.next(0, cur)) return;
; DI void layer_body(Frame& F, const int l) {
;     ...
;         REP(10) {
;         { pg8::Gemm g{Hbuf, (const bf16_t*)(F.ws + WS_WUP) + (size_t)l * 2 * DFF * D, D, D, D, 1};
;           pg8::Sched S; S.init((Mq + 251) / 252, 44, F.G, F.vcu, 0);
;           EpiConv E{(bf16_t*)(F.ws + WS_ACT), F.inp(17) + (size_t)l * 3 * 2 * DFF, F.inp(18) + (size_t)l * 2 * DFF, Mq};
;           if (PH(10)) pg8::gemm_phase(F.lds, g, S, E); }
.LBB0_1582:
	s_movk_i32 s46, 0x7e
	v_writelane_b32 v255, s0, 18
	s_mov_b32 s32, 0
	s_mov_b32 s47, 1
	s_cmp_lt_i32 s47, 1
	v_writelane_b32 v255, s1, 19
	s_cbranch_scc1 .LBB0_1691
	v_readlane_b32 s0, v254, 63
	s_or_b32 s0, s0, 0xf8
	s_mul_i32 s0, s0, 0x8209
	s_lshr_b32 s49, s0, 23
	v_readlane_b32 s0, v255, 18
	v_readlane_b32 s4, v254, 0
	v_readlane_b32 s1, v255, 19
	s_mov_b32 s2, s0
	v_readlane_b32 s6, v254, 2
	v_readlane_b32 s7, v254, 3
	s_mul_i32 s0, s0, 0x21000
	s_mul_i32 s1, s2, 0xb000
	s_mov_b64 s[2:3], s[6:7]
	v_readlane_b32 s5, v254, 1
	v_readlane_b32 s8, v254, 4
	v_readlane_b32 s9, v254, 5
	s_add_u32 s62, s2, s0
	s_mov_b64 s[4:5], s[8:9]
	s_addc_u32 s63, s3, 0
	s_add_u32 s0, s4, s1
	s_addc_u32 s1, s5, 0
	s_add_u32 s84, s62, 0xb000
	s_addc_u32 s85, s63, 0
	v_writelane_b32 v255, s0, 0
	s_add_u32 s50, s62, 0x16000
	s_mul_i32 s56, s49, 44
	v_readlane_b32 s10, v254, 6
	v_readlane_b32 s11, v254, 7
	v_writelane_b32 v255, s1, 1
	s_addc_u32 s51, s63, 0
	s_mov_b32 s48, 0
	v_writelane_b32 v254, s47, 57
	s_branch .LBB0_1587

;     DI bool next(int i, Unit& u) const { const int L = (i0 + i) * G + c - start; if (L >= 144) return false; const int bt = L >> 2; u.pm = L & 3; u.pn = (bt / 9) * 16 + (bt % 9); u.kob = 256 * u.pm; return true; }
;     DI bool next(int i, Unit& u) const {
;         const long L = (long)(i0 + i) * G + c - start; if (L >= cnt) return false;
;         const int w = (int)L, nig = 8 * nN, gid = w / nig, fm = gid * 8, gsz = (nM - fm) < 8 ? (nM - fm) : 8;
;         u.pm = fm + ((w % nig) % gsz); u.pn = (w % nig) / gsz; u.kob = kobm * u.pm; return true;
;     }
; template <class Epi, class SchedT>
; DI void gemm_phase(LAS unsigned char* lds, const Gemm g, const SchedT& S, const Epi& E) {
;     ...
;         cur = nxt; cA = nA; cB = nB; ++ui;
.LBB0_1595:
	s_mov_b32 s32, s100
	s_andn2_b64 vcc, exec, s[0:1]
	s_mov_b32 s4, s94
	s_mov_b32 s10, s56
	s_mov_b64 s[6:7], s[68:69]
	s_mov_b64 s[0:1], s[40:41]
	s_movk_i32 s68, 0x800
	s_mov_b32 s69, s73
	s_cbranch_vccz .LBB0_1636
.LBB0_1596:
	s_add_i32 s58, s58, 1
	s_add_i32 s2, s58, s57
	s_mul_hi_i32 s3, s2, s64
	s_mul_i32 s2, s2, s64
	s_add_u32 s8, s2, s69
	s_addc_u32 s9, s3, s59
	s_mov_b32 s100, 0
	s_cmp_lg_u32 s64, 0x100
	s_cbranch_scc1 .Lq8_nosplit
	s_cmp_lg_u32 s9, 0
	s_cbranch_scc1 .Lq8_nosplit
	s_and_b32 s15, s66, 0xffffff00
	s_sub_u32 s16, s66, s15
	s_cmp_eq_u32 s16, 0
	s_cbranch_scc1 .Lq8_nosplit
	s_cmp_gt_u32 s16, 0x80
	s_cbranch_scc1 .Lq8_nosplit
	s_cmp_lt_u32 s8, s15
	s_cbranch_scc1 .Lq8_nosplit
	s_cmp_le_u32 s16, 0x40
	s_cselect_b32 s16, 2, 1
	s_sub_u32 s15, s8, s15
	s_lshl_b32 s100, 1, s16
	s_sub_u32 s100, s100, 1
	s_and_b32 s100, s15, s100
	s_add_u32 s100, s100, 1
	s_lshr_b32 s15, s15, s16
	s_lshl_b32 s16, s16, 4
	s_or_b32 s100, s100, s16
	s_lshl_b32 s16, s15, 8
	s_or_b32 s100, s100, s16
	s_and_b32 s16, s66, 0xffffff00
	s_add_u32 s8, s16, s15
	s_cmp_lt_u32 s8, s66
	s_cselect_b32 s100, s100, 0
.Lq8_nosplit:
	v_mov_b64_e32 v[2:3], s[66:67]
	v_cmp_ge_i64_e32 vcc, s[8:9], v[2:3]
	v_cmp_lt_i64_e64 s[2:3], s[8:9], v[2:3]
	s_cbranch_vccnz .LBB0_1598
	s_mul_hi_i32 s5, s8, 0x2e8ba2e9
	s_lshr_b32 s9, s5, 31
	s_ashr_i32 s5, s5, 6
	s_add_i32 s5, s5, s9
	s_lshl_b32 s9, s5, 3
	s_sub_i32 s11, s49, s9
	s_min_i32 s11, s11, 8
	s_abs_i32 s12, s11
	v_cvt_f32_u32_e32 v2, s12
	s_sub_i32 s14, 0, s12
	s_mulk_i32 s5, 0x160
	s_sub_i32 s5, s8, s5
	v_rcp_iflag_f32_e32 v2, v2
	s_abs_i32 s8, s5
	s_xor_b32 s13, s5, s11
	s_ashr_i32 s13, s13, 31
	v_mul_f32_e32 v2, 0x4f7ffffe, v2
	v_cvt_u32_f32_e32 v2, v2
	s_nop 0
	v_readfirstlane_b32 s15, v2
	s_mul_i32 s14, s14, s15
	s_mul_hi_u32 s14, s15, s14
	s_add_i32 s15, s15, s14
	s_mul_hi_u32 s14, s8, s15
	s_mul_i32 s15, s14, s12
	s_sub_i32 s8, s8, s15
	s_add_i32 s16, s14, 1
	s_sub_i32 s15, s8, s12
	s_cmp_ge_u32 s8, s12
	s_cselect_b32 s14, s16, s14
	s_cselect_b32 s8, s15, s8
	s_add_i32 s15, s14, 1
	s_cmp_ge_u32 s8, s12
	s_cselect_b32 s8, s15, s14
	s_xor_b32 s8, s8, s13
	s_sub_i32 s94, s8, s13
	s_mul_i32 s8, s94, s11
	s_sub_i32 s5, s5, s8
	s_add_i32 s56, s5, s9

; #define PG8_STAGE(bufoff, gbase, voff) do { _Pragma("unroll") for (int _i = 0; _i < 2; ++_i) \
;         __builtin_amdgcn_global_load_lds((const unsigned*)((const char*)(gbase) + (voff)[_i]), (LAS unsigned*)(lds + (bufoff) + ldsw + _i * 8192), 16, 0, 0); } while (0)
; #define PG8_LDA(dst, b, h) do { _Pragma("unroll") for (int m = 0; m < 4; ++m) _Pragma("unroll") for (int k = 0; k < 2; ++k) dst[m][k] = *(const LAS bf16x8*)(lds + PG8_SA(b, h) + aoff + m * 2048 + k * 1024); } while (0)
; #define PG8_LDB(dst, b, h) do { _Pragma("unroll") for (int n = 0; n < 2; ++n) _Pragma("unroll") for (int k = 0; k < 2; ++k) dst[n][k] = *(const LAS bf16x8*)(lds + PG8_SB(b, h) + boff + n * 2048 + k * 1024); } while (0)
; #define PG8_MMA(ai, bj, At, Bt) do { __builtin_amdgcn_s_setprio(1); _Pragma("unroll") for (int m = 0; m < 4; ++m) _Pragma("unroll") for (int n = 0; n < 2; ++n) _Pragma("unroll") for (int k = 0; k < 2; ++k) \
;         acc[ai][bj][m][n] = __builtin_amdgcn_mfma_f32_16x16x32_bf16(Bt[n][k], At[m][k], acc[ai][bj][m][n], 0, 0, 0); __builtin_amdgcn_s_setprio(0); } while (0)
; #define PG8_WAIT_L(n) asm volatile("s_waitcnt lgkmcnt(" #n ")" ::: "memory")
; #define PG8_BAR __builtin_amdgcn_s_barrier()
; template <class Epi, class SchedT>
; DI void gemm_phase(LAS unsigned char* lds, const Gemm g, const SchedT& S, const Epi& E) {
;     ...
;         const char* nA = has_next ? (const char*)g.A + (size_t)nxt.pm * tstepA : cA; const char* nB = has_next ? (const char*)g.Bt + (size_t)nxt.pn * tstepB + (size_t)nxt.kob * 2 : cB;
;         for (int t = 0; t < nt; t += 2) {
;             const bool last = (t == nt - 2);
;             const char* a1 = cA + (size_t)(t + 1) * kstep;
;             const char* a2 = last ? nA : cA + (size_t)(t + 2) * kstep; const char* b2 = last ? nB : cB + (size_t)(t + 2) * kstep;
;             const char* a3 = a2 + kstep; const char* b3 = b2 + kstep;
;             PG8_LDB(B0, 0, 0); PG8_SCHED; PG8_LDA(At, 0, 0); PG8_STAGE(PG8_SA(1, 1), a1 + hstepA, voffA);
;             PG8_WAIT_L(8); PG8_BAR; PG8_WAIT_L(0); PG8_MMA(0, 0, At, B0); PG8_BAR; PG8_SCHED;
;     ...
; #pragma unroll
;         for (int a = 0; a < 2; ++a)
; #pragma unroll
;             for (int b = 0; b < 2; ++b)
; #pragma unroll
;                 for (int m = 0; m < 4; ++m)
; #pragma unroll
;                     for (int n = 0; n < 2; ++n) acc[a][b][m][n] = (f32x4){0.f, 0.f, 0.f, 0.f};
.LBB0_1600:
	s_ashr_i32 s95, s94, 31
	s_lshl_b64 s[8:9], s[94:95], 20
	s_add_u32 s68, s79, s8
	s_addc_u32 s69, s80, s9
	s_and_b32 s15, s100, 15
	s_cmp_eq_u32 s15, 0
	s_cbranch_scc1 .Lq8_noofs
	s_sub_u32 s15, s15, 1
	s_bfe_u32 s16, s100, 0x40004
	s_lshr_b32 s16, 0x1000, s16
	s_mul_i32 s15, s15, s16
	s_add_u32 s40, s40, s15
	s_addc_u32 s41, s41, 0
	s_add_u32 s68, s68, s15
	s_addc_u32 s69, s69, 0
.Lq8_noofs:
	s_and_b64 s[8:9], s[2:3], exec
	s_cselect_b32 s5, s69, s7
	s_cselect_b32 s11, s68, s6
	s_add_u32 s0, s0, 0x40080
	s_addc_u32 s1, s1, 0
	s_add_u32 s12, s6, 0x100
	v_mov_b32_e32 v2, 0
	v_mov_b32_e32 v133, v1
	v_mov_b32_e32 v131, v1
	v_mov_b32_e32 v135, v1
	s_addc_u32 s13, s7, 0
	s_mov_b32 s14, -2
	s_and_b32 s15, s32, 15
	s_cmp_eq_u32 s15, 0
	s_cbranch_scc1 .Lq8_fullk
	s_bfe_u32 s15, s32, 0x40004
	s_lshr_b32 s15, 32, s15
	s_sub_u32 s14, 30, s15
.Lq8_fullk:
	v_mov_b32_e32 v3, v2
	v_mov_b32_e32 v4, v2
	v_mov_b32_e32 v5, v2
	v_mov_b32_e32 v66, v2
	v_mov_b32_e32 v67, v2
	v_mov_b32_e32 v68, v2
	v_mov_b32_e32 v69, v2
	v_mov_b32_e32 v6, v2
	v_mov_b32_e32 v7, v2
	v_mov_b32_e32 v8, v2
	v_mov_b32_e32 v9, v2
	v_mov_b32_e32 v70, v2
	v_mov_b32_e32 v71, v2
	v_mov_b32_e32 v72, v2
	v_mov_b32_e32 v73, v2
	v_mov_b32_e32 v10, v2
	v_mov_b32_e32 v11, v2
	v_mov_b32_e32 v12, v2
	v_mov_b32_e32 v13, v2
	v_mov_b32_e32 v74, v2
	v_mov_b32_e32 v75, v2
	v_mov_b32_e32 v76, v2
	v_mov_b32_e32 v77, v2
	v_mov_b32_e32 v14, v2
	v_mov_b32_e32 v15, v2
	s_waitcnt vmcnt(0)
	v_mov_b32_e32 v16, v2
	v_mov_b32_e32 v17, v2
	v_mov_b32_e32 v78, v2
	v_mov_b32_e32 v79, v2
	v_mov_b32_e32 v80, v2
	v_mov_b32_e32 v81, v2
	v_mov_b32_e32 v34, v2
	v_mov_b32_e32 v35, v2
	v_mov_b32_e32 v36, v2
	v_mov_b32_e32 v37, v2
	v_mov_b32_e32 v98, v2
	v_mov_b32_e32 v99, v2
	v_mov_b32_e32 v100, v2
	v_mov_b32_e32 v101, v2
	v_mov_b32_e32 v38, v2
	v_mov_b32_e32 v39, v2
	v_mov_b32_e32 v40, v2
	v_mov_b32_e32 v41, v2
	v_mov_b32_e32 v102, v2
	v_mov_b32_e32 v103, v2
	v_mov_b32_e32 v104, v2
	v_mov_b32_e32 v105, v2
	v_mov_b32_e32 v42, v2
	v_mov_b32_e32 v43, v2
	v_mov_b32_e32 v44, v2
	v_mov_b32_e32 v45, v2
	v_mov_b32_e32 v106, v2
	v_mov_b32_e32 v107, v2
	v_mov_b32_e32 v108, v2
	v_mov_b32_e32 v109, v2
	v_mov_b32_e32 v46, v2
	v_mov_b32_e32 v47, v2
	v_mov_b32_e32 v48, v2
	v_mov_b32_e32 v49, v2
	v_mov_b32_e32 v110, v2
	v_mov_b32_e32 v111, v2
	v_mov_b32_e32 v112, v2
	v_mov_b32_e32 v113, v2
	v_mov_b32_e32 v18, v2
	v_mov_b32_e32 v19, v2
	v_mov_b32_e32 v20, v2
	v_mov_b32_e32 v21, v2
	v_mov_b32_e32 v82, v2
	v_mov_b32_e32 v83, v2
	v_mov_b32_e32 v84, v2
	v_mov_b32_e32 v85, v2
	v_mov_b32_e32 v22, v2
	v_mov_b32_e32 v23, v2
	v_mov_b32_e32 v24, v2
	v_mov_b32_e32 v25, v2
	v_mov_b32_e32 v86, v2
	v_mov_b32_e32 v87, v2
	v_mov_b32_e32 v88, v2
	v_mov_b32_e32 v89, v2
	v_mov_b32_e32 v26, v2
	v_mov_b32_e32 v27, v2
	v_mov_b32_e32 v28, v2
	v_mov_b32_e32 v29, v2
	v_mov_b32_e32 v90, v2
	v_mov_b32_e32 v91, v2
	v_mov_b32_e32 v92, v2
	v_mov_b32_e32 v93, v2
	v_mov_b32_e32 v30, v2
	v_mov_b32_e32 v31, v2
	v_mov_b32_e32 v32, v2
	v_mov_b32_e32 v33, v2
	v_mov_b32_e32 v94, v2
	v_mov_b32_e32 v95, v2
	v_mov_b32_e32 v96, v2
	v_mov_b32_e32 v97, v2
	v_mov_b32_e32 v50, v2
	v_mov_b32_e32 v51, v2
	v_mov_b32_e32 v52, v2
	v_mov_b32_e32 v53, v2
	v_mov_b32_e32 v114, v2
	v_mov_b32_e32 v115, v2
	v_mov_b32_e32 v116, v2
	v_mov_b32_e32 v117, v2
	v_mov_b32_e32 v54, v2
	v_mov_b32_e32 v55, v2
	v_mov_b32_e32 v56, v2
	v_mov_b32_e32 v57, v2
	v_mov_b32_e32 v118, v2
	v_mov_b32_e32 v119, v2
	v_mov_b32_e32 v120, v2
	v_mov_b32_e32 v121, v2
	v_mov_b32_e32 v58, v2
	v_mov_b32_e32 v59, v2
	v_mov_b32_e32 v60, v2
	v_mov_b32_e32 v61, v2
	v_mov_b32_e32 v122, v2
	v_mov_b32_e32 v123, v2
	v_mov_b32_e32 v124, v2
	v_mov_b32_e32 v125, v2
	v_mov_b32_e32 v62, v2
	v_mov_b32_e32 v63, v2
	v_mov_b32_e32 v64, v2
	v_mov_b32_e32 v65, v2
	v_mov_b32_e32 v126, v2
	v_mov_b32_e32 v127, v2
	v_mov_b32_e32 v128, v2
	v_mov_b32_e32 v129, v2
.LBB0_1601:
	s_add_u32 s6, s0, 0xfffc0080
	s_addc_u32 s7, s1, -1
	s_add_i32 s15, 0, 0x10000
	v_add_u32_e32 v148, s15, v186
	ds_read_b128 v[136:139], v148
	ds_read_b128 v[140:143], v148 offset:1024
	ds_read_b128 v[144:147], v148 offset:2048
	ds_read_b128 v[148:151], v148 offset:3072
	s_cmp_eq_u32 s14, 28
	s_cselect_b32 s9, s41, s7
	s_cselect_b32 s8, s40, s6
	s_cselect_b32 s7, s5, s13
	s_cselect_b32 s6, s11, s12
	v_lshl_add_u64 v[180:181], s[0:1], 0, v[0:1]
	s_add_i32 m0, s81, 0xc000
	ds_read_b128 v[152:155], v187
	ds_read_b128 v[156:159], v187 offset:1024
	ds_read_b128 v[160:163], v187 offset:2048
	ds_read_b128 v[164:167], v187 offset:3072
	ds_read_b128 v[168:171], v187 offset:4096
	ds_read_b128 v[172:175], v187 offset:5120
	ds_read_b128 v[176:179], v187 offset:6144
	ds_read_b128 v[188:191], v187 offset:7168
	global_load_lds_dwordx4 v[180:181], off
	v_lshl_add_u64 v[180:181], s[0:1], 0, v[132:133]
	s_add_i32 m0, s81, 0xe000
	s_nop 0
	global_load_lds_dwordx4 v[180:181], off
	s_waitcnt lgkmcnt(8)
	s_barrier
	s_waitcnt lgkmcnt(0)
	s_setprio 1
	s_waitcnt lgkmcnt(0)
	v_mfma_f32_16x16x32_bf16 v[126:129], v[136:139], v[152:155], v[126:129]
	v_mfma_f32_16x16x32_bf16 v[62:65], v[144:147], v[152:155], v[62:65]
	v_mfma_f32_16x16x32_bf16 v[122:125], v[136:139], v[160:163], v[122:125]
	v_mfma_f32_16x16x32_bf16 v[58:61], v[144:147], v[160:163], v[58:61]
	v_mfma_f32_16x16x32_bf16 v[118:121], v[136:139], v[168:171], v[118:121]
	v_mfma_f32_16x16x32_bf16 v[54:57], v[144:147], v[168:171], v[54:57]
	v_mfma_f32_16x16x32_bf16 v[114:117], v[136:139], v[176:179], v[114:117]
	v_mfma_f32_16x16x32_bf16 v[50:53], v[144:147], v[176:179], v[50:53]
	v_mfma_f32_16x16x32_bf16 v[126:129], v[140:143], v[156:159], v[126:129]
	v_mfma_f32_16x16x32_bf16 v[62:65], v[148:151], v[156:159], v[62:65]
	v_mfma_f32_16x16x32_bf16 v[122:125], v[140:143], v[164:167], v[122:125]
	v_mfma_f32_16x16x32_bf16 v[58:61], v[148:151], v[164:167], v[58:61]
	v_mfma_f32_16x16x32_bf16 v[118:121], v[140:143], v[172:175], v[118:121]
	v_mfma_f32_16x16x32_bf16 v[54:57], v[148:151], v[172:175], v[54:57]
	v_mfma_f32_16x16x32_bf16 v[114:117], v[140:143], v[188:191], v[114:117]
	v_mfma_f32_16x16x32_bf16 v[50:53], v[148:151], v[188:191], v[50:53]
	s_setprio 0
	s_barrier
; #define PG8_STAGE(bufoff, gbase, voff) do { _Pragma("unroll") for (int _i = 0; _i < 2; ++_i) \
;         __builtin_amdgcn_global_load_lds((const unsigned*)((const char*)(gbase) + (voff)[_i]), (LAS unsigned*)(lds + (bufoff) + ldsw + _i * 8192), 16, 0, 0); } while (0)
; #define PG8_LDA(dst, b, h) do { _Pragma("unroll") for (int m = 0; m < 4; ++m) _Pragma("unroll") for (int k = 0; k < 2; ++k) dst[m][k] = *(const LAS bf16x8*)(lds + PG8_SA(b, h) + aoff + m * 2048 + k * 1024); } while (0)
; #define PG8_LDB(dst, b, h) do { _Pragma("unroll") for (int n = 0; n < 2; ++n) _Pragma("unroll") for (int k = 0; k < 2; ++k) dst[n][k] = *(const LAS bf16x8*)(lds + PG8_SB(b, h) + boff + n * 2048 + k * 1024); } while (0)
; #define PG8_MMA(ai, bj, At, Bt) do { __builtin_amdgcn_s_setprio(1); _Pragma("unroll") for (int m = 0; m < 4; ++m) _Pragma("unroll") for (int n = 0; n < 2; ++n) _Pragma("unroll") for (int k = 0; k < 2; ++k) \
;         acc[ai][bj][m][n] = __builtin_amdgcn_mfma_f32_16x16x32_bf16(Bt[n][k], At[m][k], acc[ai][bj][m][n], 0, 0, 0); __builtin_amdgcn_s_setprio(0); } while (0)
; #define PG8_WAIT_V(n) asm volatile("s_waitcnt vmcnt(" #n ")" ::: "memory")
; #define PG8_WAIT_L(n) asm volatile("s_waitcnt lgkmcnt(" #n ")" ::: "memory")
; #define PG8_BAR __builtin_amdgcn_s_barrier()
; #define PG8_SCHED __builtin_amdgcn_sched_barrier(0)
; template <class Epi, class SchedT>
; DI void gemm_phase(LAS unsigned char* lds, const Gemm g, const SchedT& S, const Epi& E) {
;     ...
;             PG8_LDB(B1, 0, 1); PG8_STAGE(PG8_SB(0, 0), b2, voffB);
;             PG8_BAR; PG8_WAIT_L(0); PG8_MMA(0, 1, At, B1); PG8_BAR;
;             PG8_LDA(At, 0, 1); PG8_STAGE(PG8_SA(0, 0), a2, voffA);
;             PG8_BAR; PG8_WAIT_L(0); PG8_MMA(1, 0, At, B0); PG8_BAR; PG8_SCHED;
;             PG8_STAGE(PG8_SB(0, 1), b2 + hstepB, voffB);
;             PG8_WAIT_V(6); PG8_BAR; PG8_MMA(1, 1, At, B1); PG8_BAR;
;             PG8_LDB(B0, 1, 0); PG8_SCHED; PG8_LDA(At, 1, 0); PG8_STAGE(PG8_SA(0, 1), a2 + hstepA, voffA);
;             PG8_WAIT_L(8); PG8_BAR; PG8_WAIT_L(0); PG8_MMA(0, 0, At, B0); PG8_BAR; PG8_SCHED;
	s_add_i32 s18, 0, 0x14000
	v_add_u32_e32 v180, s18, v186
	s_add_i32 s15, s15, s76
	ds_read_b128 v[202:205], v180
	ds_read_b128 v[206:209], v180 offset:1024
	ds_read_b128 v[210:213], v180 offset:2048
	ds_read_b128 v[214:217], v180 offset:3072
	v_lshl_add_u64 v[180:181], s[6:7], 0, v[130:131]
	s_mov_b32 m0, s15
	v_lshl_add_u64 v[182:183], s[6:7], 0, v[134:135]
	global_load_lds_dwordx4 v[180:181], off
	s_add_i32 m0, s15, 0x2000
	s_nop 0
	global_load_lds_dwordx4 v[182:183], off
	s_barrier
	s_waitcnt lgkmcnt(0)
	s_setprio 1
	s_waitcnt lgkmcnt(0)
	v_mfma_f32_16x16x32_bf16 v[94:97], v[202:205], v[152:155], v[94:97]
	v_mfma_f32_16x16x32_bf16 v[30:33], v[210:213], v[152:155], v[30:33]
	v_mfma_f32_16x16x32_bf16 v[90:93], v[202:205], v[160:163], v[90:93]
	v_mfma_f32_16x16x32_bf16 v[26:29], v[210:213], v[160:163], v[26:29]
	v_mfma_f32_16x16x32_bf16 v[86:89], v[202:205], v[168:171], v[86:89]
	v_mfma_f32_16x16x32_bf16 v[22:25], v[210:213], v[168:171], v[22:25]
	v_mfma_f32_16x16x32_bf16 v[82:85], v[202:205], v[176:179], v[82:85]
	v_mfma_f32_16x16x32_bf16 v[18:21], v[210:213], v[176:179], v[18:21]
	v_mfma_f32_16x16x32_bf16 v[94:97], v[206:209], v[156:159], v[94:97]
	v_mfma_f32_16x16x32_bf16 v[30:33], v[214:217], v[156:159], v[30:33]
	v_mfma_f32_16x16x32_bf16 v[90:93], v[206:209], v[164:167], v[90:93]
	v_mfma_f32_16x16x32_bf16 v[26:29], v[214:217], v[164:167], v[26:29]
	v_mfma_f32_16x16x32_bf16 v[86:89], v[206:209], v[172:175], v[86:89]
	v_mfma_f32_16x16x32_bf16 v[22:25], v[214:217], v[172:175], v[22:25]
	v_mfma_f32_16x16x32_bf16 v[82:85], v[206:209], v[188:191], v[82:85]
	v_mfma_f32_16x16x32_bf16 v[18:21], v[214:217], v[188:191], v[18:21]
	s_setprio 0
	s_mov_b32 m0, s81
	v_lshl_add_u64 v[194:195], s[8:9], 0, v[0:1]
	s_barrier
	ds_read_b128 v[152:155], v187 offset:16384
	ds_read_b128 v[156:159], v187 offset:17408
	ds_read_b128 v[160:163], v187 offset:18432
	ds_read_b128 v[164:167], v187 offset:19456
	ds_read_b128 v[168:171], v187 offset:20480
	ds_read_b128 v[172:175], v187 offset:21504
	ds_read_b128 v[176:179], v187 offset:22528
	ds_read_b128 v[188:191], v187 offset:23552
	global_load_lds_dwordx4 v[194:195], off
	v_lshl_add_u64 v[196:197], s[8:9], 0, v[132:133]
	s_mov_b32 m0, s82
	s_nop 0
	global_load_lds_dwordx4 v[196:197], off
	s_barrier
	s_waitcnt lgkmcnt(0)
	s_setprio 1
	s_waitcnt lgkmcnt(0)
	v_mfma_f32_16x16x32_bf16 v[110:113], v[136:139], v[152:155], v[110:113]
	v_mfma_f32_16x16x32_bf16 v[46:49], v[144:147], v[152:155], v[46:49]
	v_mfma_f32_16x16x32_bf16 v[106:109], v[136:139], v[160:163], v[106:109]
	v_mfma_f32_16x16x32_bf16 v[42:45], v[144:147], v[160:163], v[42:45]
	v_mfma_f32_16x16x32_bf16 v[102:105], v[136:139], v[168:171], v[102:105]
	v_mfma_f32_16x16x32_bf16 v[38:41], v[144:147], v[168:171], v[38:41]
	v_mfma_f32_16x16x32_bf16 v[98:101], v[136:139], v[176:179], v[98:101]
	v_mfma_f32_16x16x32_bf16 v[34:37], v[144:147], v[176:179], v[34:37]
	v_mfma_f32_16x16x32_bf16 v[110:113], v[140:143], v[156:159], v[110:113]
	v_mfma_f32_16x16x32_bf16 v[46:49], v[148:151], v[156:159], v[46:49]
	v_mfma_f32_16x16x32_bf16 v[106:109], v[140:143], v[164:167], v[106:109]
	v_mfma_f32_16x16x32_bf16 v[42:45], v[148:151], v[164:167], v[42:45]
	v_mfma_f32_16x16x32_bf16 v[102:105], v[140:143], v[172:175], v[102:105]
	v_mfma_f32_16x16x32_bf16 v[38:41], v[148:151], v[172:175], v[38:41]
	v_mfma_f32_16x16x32_bf16 v[98:101], v[140:143], v[188:191], v[98:101]
	v_mfma_f32_16x16x32_bf16 v[34:37], v[148:151], v[188:191], v[34:37]
	s_setprio 0
	s_barrier
	s_add_u32 s16, s6, 0x80000
	s_addc_u32 s17, s7, 0
	s_add_i32 s15, s18, s76
	v_lshl_add_u64 v[136:137], s[16:17], 0, v[130:131]
	s_mov_b32 m0, s15
	s_nop 0
	global_load_lds_dwordx4 v[136:137], off
	v_lshl_add_u64 v[136:137], s[16:17], 0, v[134:135]
	s_add_i32 m0, s15, 0x2000
	s_nop 0
	global_load_lds_dwordx4 v[136:137], off
	s_waitcnt vmcnt(6)
	s_barrier
	s_setprio 1
	v_mfma_f32_16x16x32_bf16 v[78:81], v[202:205], v[152:155], v[78:81]
	v_mfma_f32_16x16x32_bf16 v[14:17], v[210:213], v[152:155], v[14:17]
	v_mfma_f32_16x16x32_bf16 v[74:77], v[202:205], v[160:163], v[74:77]
	v_mfma_f32_16x16x32_bf16 v[10:13], v[210:213], v[160:163], v[10:13]
	v_mfma_f32_16x16x32_bf16 v[70:73], v[202:205], v[168:171], v[70:73]
	v_mfma_f32_16x16x32_bf16 v[6:9], v[210:213], v[168:171], v[6:9]
	v_mfma_f32_16x16x32_bf16 v[66:69], v[202:205], v[176:179], v[66:69]
	v_mfma_f32_16x16x32_bf16 v[2:5], v[210:213], v[176:179], v[2:5]
	v_mfma_f32_16x16x32_bf16 v[78:81], v[206:209], v[156:159], v[78:81]
	v_mfma_f32_16x16x32_bf16 v[14:17], v[214:217], v[156:159], v[14:17]
	v_mfma_f32_16x16x32_bf16 v[74:77], v[206:209], v[164:167], v[74:77]
	v_mfma_f32_16x16x32_bf16 v[10:13], v[214:217], v[164:167], v[10:13]
	v_mfma_f32_16x16x32_bf16 v[70:73], v[206:209], v[172:175], v[70:73]
	v_mfma_f32_16x16x32_bf16 v[6:9], v[214:217], v[172:175], v[6:9]
	v_mfma_f32_16x16x32_bf16 v[66:69], v[206:209], v[188:191], v[66:69]
	v_mfma_f32_16x16x32_bf16 v[2:5], v[214:217], v[188:191], v[2:5]
	s_setprio 0
	s_add_i32 s15, 0, 0x18000
	v_add_u32_e32 v148, s15, v186
	s_barrier
	ds_read_b128 v[136:139], v148
	ds_read_b128 v[140:143], v148 offset:1024
	ds_read_b128 v[144:147], v148 offset:2048
	ds_read_b128 v[148:151], v148 offset:3072
	s_add_u32 s8, s8, 0x40000
	s_addc_u32 s9, s9, 0
	s_mov_b32 m0, s83
	v_lshl_add_u64 v[198:199], s[8:9], 0, v[0:1]
	ds_read_b128 v[152:155], v187 offset:32768
	ds_read_b128 v[156:159], v187 offset:33792
	ds_read_b128 v[160:163], v187 offset:34816
	ds_read_b128 v[164:167], v187 offset:35840
	ds_read_b128 v[168:171], v187 offset:36864
	ds_read_b128 v[172:175], v187 offset:37888
	ds_read_b128 v[176:179], v187 offset:38912
	ds_read_b128 v[188:191], v187 offset:39936
	global_load_lds_dwordx4 v[198:199], off
	v_lshl_add_u64 v[198:199], s[8:9], 0, v[132:133]
	s_mov_b32 m0, s88
	s_nop 0
	global_load_lds_dwordx4 v[198:199], off
	s_waitcnt lgkmcnt(8)
	s_barrier
; #define PG8_STAGE(bufoff, gbase, voff) do { _Pragma("unroll") for (int _i = 0; _i < 2; ++_i) \
;         __builtin_amdgcn_global_load_lds((const unsigned*)((const char*)(gbase) + (voff)[_i]), (LAS unsigned*)(lds + (bufoff) + ldsw + _i * 8192), 16, 0, 0); } while (0)
; #define PG8_LDA(dst, b, h) do { _Pragma("unroll") for (int m = 0; m < 4; ++m) _Pragma("unroll") for (int k = 0; k < 2; ++k) dst[m][k] = *(const LAS bf16x8*)(lds + PG8_SA(b, h) + aoff + m * 2048 + k * 1024); } while (0)
; #define PG8_LDB(dst, b, h) do { _Pragma("unroll") for (int n = 0; n < 2; ++n) _Pragma("unroll") for (int k = 0; k < 2; ++k) dst[n][k] = *(const LAS bf16x8*)(lds + PG8_SB(b, h) + boff + n * 2048 + k * 1024); } while (0)
; #define PG8_MMA(ai, bj, At, Bt) do { __builtin_amdgcn_s_setprio(1); _Pragma("unroll") for (int m = 0; m < 4; ++m) _Pragma("unroll") for (int n = 0; n < 2; ++n) _Pragma("unroll") for (int k = 0; k < 2; ++k) \
;         acc[ai][bj][m][n] = __builtin_amdgcn_mfma_f32_16x16x32_bf16(Bt[n][k], At[m][k], acc[ai][bj][m][n], 0, 0, 0); __builtin_amdgcn_s_setprio(0); } while (0)
; #define PG8_WAIT_V(n) asm volatile("s_waitcnt vmcnt(" #n ")" ::: "memory")
; #define PG8_WAIT_L(n) asm volatile("s_waitcnt lgkmcnt(" #n ")" ::: "memory")
; #define PG8_BAR __builtin_amdgcn_s_barrier()
; #define PG8_SCHED __builtin_amdgcn_sched_barrier(0)
; template <class Epi, class SchedT>
; DI void gemm_phase(LAS unsigned char* lds, const Gemm g, const SchedT& S, const Epi& E) {
;     ...
;             PG8_LDB(B0, 1, 0); PG8_SCHED; PG8_LDA(At, 1, 0); PG8_STAGE(PG8_SA(0, 1), a2 + hstepA, voffA);
;             PG8_WAIT_L(8); PG8_BAR; PG8_WAIT_L(0); PG8_MMA(0, 0, At, B0); PG8_BAR; PG8_SCHED;
;             PG8_LDB(B1, 1, 1); PG8_STAGE(PG8_SB(1, 0), b3, voffB);
;             PG8_BAR; PG8_WAIT_L(0); PG8_MMA(0, 1, At, B1); PG8_BAR;
;             PG8_LDA(At, 1, 1); PG8_STAGE(PG8_SA(1, 0), a3, voffA);
;             PG8_BAR; PG8_WAIT_L(0); PG8_MMA(1, 0, At, B0); PG8_BAR; PG8_SCHED;
;             PG8_STAGE(PG8_SB(1, 1), b3 + hstepB, voffB);
;             PG8_WAIT_V(6); PG8_BAR; PG8_MMA(1, 1, At, B1); PG8_BAR;
;         }
	s_waitcnt lgkmcnt(0)
	s_setprio 1
	s_waitcnt lgkmcnt(0)
	v_mfma_f32_16x16x32_bf16 v[126:129], v[136:139], v[152:155], v[126:129]
	v_mfma_f32_16x16x32_bf16 v[62:65], v[144:147], v[152:155], v[62:65]
	v_mfma_f32_16x16x32_bf16 v[122:125], v[136:139], v[160:163], v[122:125]
	v_mfma_f32_16x16x32_bf16 v[58:61], v[144:147], v[160:163], v[58:61]
	v_mfma_f32_16x16x32_bf16 v[118:121], v[136:139], v[168:171], v[118:121]
	v_mfma_f32_16x16x32_bf16 v[54:57], v[144:147], v[168:171], v[54:57]
	v_mfma_f32_16x16x32_bf16 v[114:117], v[136:139], v[176:179], v[114:117]
	v_mfma_f32_16x16x32_bf16 v[50:53], v[144:147], v[176:179], v[50:53]
	v_mfma_f32_16x16x32_bf16 v[126:129], v[140:143], v[156:159], v[126:129]
	v_mfma_f32_16x16x32_bf16 v[62:65], v[148:151], v[156:159], v[62:65]
	v_mfma_f32_16x16x32_bf16 v[122:125], v[140:143], v[164:167], v[122:125]
	v_mfma_f32_16x16x32_bf16 v[58:61], v[148:151], v[164:167], v[58:61]
	v_mfma_f32_16x16x32_bf16 v[118:121], v[140:143], v[172:175], v[118:121]
	v_mfma_f32_16x16x32_bf16 v[54:57], v[148:151], v[172:175], v[54:57]
	v_mfma_f32_16x16x32_bf16 v[114:117], v[140:143], v[188:191], v[114:117]
	v_mfma_f32_16x16x32_bf16 v[50:53], v[148:151], v[188:191], v[50:53]
	s_setprio 0
	s_barrier
	s_add_i32 s8, 0, 0x1c000
	s_add_i32 s9, s15, s76
	v_add_u32_e32 v198, s8, v186
	v_lshl_add_u64 v[180:181], v[180:181], 0, s[90:91]
	s_mov_b32 m0, s9
	ds_read_b128 v[202:205], v198
	ds_read_b128 v[206:209], v198 offset:1024
	ds_read_b128 v[210:213], v198 offset:2048
	ds_read_b128 v[214:217], v198 offset:3072
	global_load_lds_dwordx4 v[180:181], off
	v_lshl_add_u64 v[180:181], v[182:183], 0, s[90:91]
	s_add_i32 m0, s9, 0x2000
	s_nop 0
	global_load_lds_dwordx4 v[180:181], off
	s_barrier
	s_waitcnt lgkmcnt(0)
	s_setprio 1
	s_waitcnt lgkmcnt(0)
	v_mfma_f32_16x16x32_bf16 v[94:97], v[202:205], v[152:155], v[94:97]
	v_mfma_f32_16x16x32_bf16 v[30:33], v[210:213], v[152:155], v[30:33]
	v_mfma_f32_16x16x32_bf16 v[90:93], v[202:205], v[160:163], v[90:93]
	v_mfma_f32_16x16x32_bf16 v[26:29], v[210:213], v[160:163], v[26:29]
	v_mfma_f32_16x16x32_bf16 v[86:89], v[202:205], v[168:171], v[86:89]
	v_mfma_f32_16x16x32_bf16 v[22:25], v[210:213], v[168:171], v[22:25]
	v_mfma_f32_16x16x32_bf16 v[82:85], v[202:205], v[176:179], v[82:85]
	v_mfma_f32_16x16x32_bf16 v[18:21], v[210:213], v[176:179], v[18:21]
	v_mfma_f32_16x16x32_bf16 v[94:97], v[206:209], v[156:159], v[94:97]
	v_mfma_f32_16x16x32_bf16 v[30:33], v[214:217], v[156:159], v[30:33]
	v_mfma_f32_16x16x32_bf16 v[90:93], v[206:209], v[164:167], v[90:93]
	v_mfma_f32_16x16x32_bf16 v[26:29], v[214:217], v[164:167], v[26:29]
	v_mfma_f32_16x16x32_bf16 v[86:89], v[206:209], v[172:175], v[86:89]
	v_mfma_f32_16x16x32_bf16 v[22:25], v[214:217], v[172:175], v[22:25]
	v_mfma_f32_16x16x32_bf16 v[82:85], v[206:209], v[188:191], v[82:85]
	v_mfma_f32_16x16x32_bf16 v[18:21], v[214:217], v[188:191], v[18:21]
	s_setprio 0
	s_mov_b32 m0, s47
	v_lshl_add_u64 v[180:181], v[194:195], 0, s[90:91]
	s_barrier
	ds_read_b128 v[152:155], v187 offset:49152
	ds_read_b128 v[156:159], v187 offset:50176
	ds_read_b128 v[160:163], v187 offset:51200
	ds_read_b128 v[164:167], v187 offset:52224
	ds_read_b128 v[168:171], v187 offset:53248
	ds_read_b128 v[172:175], v187 offset:54272
	ds_read_b128 v[176:179], v187 offset:55296
	ds_read_b128 v[188:191], v187 offset:56320
	global_load_lds_dwordx4 v[180:181], off
	v_lshl_add_u64 v[180:181], v[196:197], 0, s[90:91]
	s_mov_b32 m0, s48
	s_nop 0
	global_load_lds_dwordx4 v[180:181], off
	s_barrier
	s_waitcnt lgkmcnt(0)
	s_setprio 1
	s_waitcnt lgkmcnt(0)
	v_mfma_f32_16x16x32_bf16 v[110:113], v[136:139], v[152:155], v[110:113]
	v_mfma_f32_16x16x32_bf16 v[46:49], v[144:147], v[152:155], v[46:49]
	v_mfma_f32_16x16x32_bf16 v[106:109], v[136:139], v[160:163], v[106:109]
	v_mfma_f32_16x16x32_bf16 v[42:45], v[144:147], v[160:163], v[42:45]
	v_mfma_f32_16x16x32_bf16 v[102:105], v[136:139], v[168:171], v[102:105]
	v_mfma_f32_16x16x32_bf16 v[38:41], v[144:147], v[168:171], v[38:41]
	v_mfma_f32_16x16x32_bf16 v[98:101], v[136:139], v[176:179], v[98:101]
	v_mfma_f32_16x16x32_bf16 v[34:37], v[144:147], v[176:179], v[34:37]
	v_mfma_f32_16x16x32_bf16 v[110:113], v[140:143], v[156:159], v[110:113]
	v_mfma_f32_16x16x32_bf16 v[46:49], v[148:151], v[156:159], v[46:49]
	v_mfma_f32_16x16x32_bf16 v[106:109], v[140:143], v[164:167], v[106:109]
	v_mfma_f32_16x16x32_bf16 v[42:45], v[148:151], v[164:167], v[42:45]
	v_mfma_f32_16x16x32_bf16 v[102:105], v[140:143], v[172:175], v[102:105]
	v_mfma_f32_16x16x32_bf16 v[38:41], v[148:151], v[172:175], v[38:41]
	v_mfma_f32_16x16x32_bf16 v[98:101], v[140:143], v[188:191], v[98:101]
	v_mfma_f32_16x16x32_bf16 v[34:37], v[148:151], v[188:191], v[34:37]
	s_setprio 0
	s_barrier
	s_add_u32 s6, s6, 0x80080
	s_addc_u32 s7, s7, 0
	s_add_i32 s8, s8, s76
	v_lshl_add_u64 v[136:137], s[6:7], 0, v[130:131]
	s_mov_b32 m0, s8
	s_nop 0
	global_load_lds_dwordx4 v[136:137], off
	v_lshl_add_u64 v[136:137], s[6:7], 0, v[134:135]
	s_add_i32 m0, s8, 0x2000
	s_nop 0
	global_load_lds_dwordx4 v[136:137], off
	s_waitcnt vmcnt(6)
	s_barrier
	s_setprio 1
	v_mfma_f32_16x16x32_bf16 v[78:81], v[202:205], v[152:155], v[78:81]
	v_mfma_f32_16x16x32_bf16 v[14:17], v[210:213], v[152:155], v[14:17]
	v_mfma_f32_16x16x32_bf16 v[74:77], v[202:205], v[160:163], v[74:77]
	v_mfma_f32_16x16x32_bf16 v[10:13], v[210:213], v[160:163], v[10:13]
	v_mfma_f32_16x16x32_bf16 v[70:73], v[202:205], v[168:171], v[70:73]
	v_mfma_f32_16x16x32_bf16 v[6:9], v[210:213], v[168:171], v[6:9]
	v_mfma_f32_16x16x32_bf16 v[66:69], v[202:205], v[176:179], v[66:69]
	v_mfma_f32_16x16x32_bf16 v[2:5], v[210:213], v[176:179], v[2:5]
	v_mfma_f32_16x16x32_bf16 v[78:81], v[206:209], v[156:159], v[78:81]
	v_mfma_f32_16x16x32_bf16 v[14:17], v[214:217], v[156:159], v[14:17]
	v_mfma_f32_16x16x32_bf16 v[74:77], v[206:209], v[164:167], v[74:77]
	v_mfma_f32_16x16x32_bf16 v[10:13], v[214:217], v[164:167], v[10:13]
	v_mfma_f32_16x16x32_bf16 v[70:73], v[206:209], v[172:175], v[70:73]
	v_mfma_f32_16x16x32_bf16 v[6:9], v[214:217], v[172:175], v[6:9]
	v_mfma_f32_16x16x32_bf16 v[66:69], v[206:209], v[188:191], v[66:69]
	v_mfma_f32_16x16x32_bf16 v[2:5], v[214:217], v[188:191], v[2:5]
	s_setprio 0
	s_add_i32 s14, s14, 2
	s_add_u32 s0, s0, 0x100
	s_addc_u32 s1, s1, 0
	s_add_u32 s12, s12, 0x100
	s_addc_u32 s13, s13, 0
	s_cmp_gt_u32 s14, 29
	s_barrier
	s_cbranch_scc0 .LBB0_1601
	s_and_b32 s8, s32, 15
	s_cmp_eq_u32 s8, 0
	s_cbranch_scc1 .Lq8_epi_normal
	s_cmp_eq_u32 s65, 0
	s_cbranch_scc0 .Lq8_al0
	s_barrier
; template <class Epi, class SchedT>
; DI void gemm_phase(LAS unsigned char* lds, const Gemm g, const SchedT& S, const Epi& E) {
;     ...
;         { int fr2 = fr, fq2 = fq, wr2 = wr, wc2 = wc; asm volatile("" : "+v"(fr2), "+v"(fq2), "+s"(wr2), "+s"(wc2));
;           E(acc, cur, wr2, wc2, fr2, fq2); }
.Lq8_al0:
	s_lshr_b32 s9, s32, 8
	s_bfe_u32 s6, s32, 0x40004
	s_lshl_b32 s7, s9, s6
	s_sub_u32 s8, s8, 1
	s_add_u32 s8, s7, s8
	s_lshl_b32 s8, s8, 18
	s_sub_u32 s0, s92, 0x4600000
	s_subb_u32 s1, s93, 0
	s_add_u32 s0, s0, s8
	s_addc_u32 s1, s1, 0
	v_lshlrev_b32_e32 v250, 4, v192
	global_store_dwordx4 v250, v[2:5], s[0:1] sc0 sc1
	s_add_u32 s0, s0, 0x2000
	s_addc_u32 s1, s1, 0
	global_store_dwordx4 v250, v[6:9], s[0:1] sc0 sc1
	s_add_u32 s0, s0, 0x2000
	s_addc_u32 s1, s1, 0
	global_store_dwordx4 v250, v[10:13], s[0:1] sc0 sc1
	s_add_u32 s0, s0, 0x2000
	s_addc_u32 s1, s1, 0
	global_store_dwordx4 v250, v[14:17], s[0:1] sc0 sc1
	s_add_u32 s0, s0, 0x2000
	s_addc_u32 s1, s1, 0
	global_store_dwordx4 v250, v[18:21], s[0:1] sc0 sc1
	s_add_u32 s0, s0, 0x2000
	s_addc_u32 s1, s1, 0
	global_store_dwordx4 v250, v[22:25], s[0:1] sc0 sc1
	s_add_u32 s0, s0, 0x2000
	s_addc_u32 s1, s1, 0
	global_store_dwordx4 v250, v[26:29], s[0:1] sc0 sc1
	s_add_u32 s0, s0, 0x2000
	s_addc_u32 s1, s1, 0
	global_store_dwordx4 v250, v[30:33], s[0:1] sc0 sc1
	s_add_u32 s0, s0, 0x2000
	s_addc_u32 s1, s1, 0
	global_store_dwordx4 v250, v[34:37], s[0:1] sc0 sc1
	s_add_u32 s0, s0, 0x2000
	s_addc_u32 s1, s1, 0
	global_store_dwordx4 v250, v[38:41], s[0:1] sc0 sc1
	s_add_u32 s0, s0, 0x2000
	s_addc_u32 s1, s1, 0
	global_store_dwordx4 v250, v[42:45], s[0:1] sc0 sc1
	s_add_u32 s0, s0, 0x2000
	s_addc_u32 s1, s1, 0
	global_store_dwordx4 v250, v[46:49], s[0:1] sc0 sc1
	s_add_u32 s0, s0, 0x2000
	s_addc_u32 s1, s1, 0
	global_store_dwordx4 v250, v[50:53], s[0:1] sc0 sc1
	s_add_u32 s0, s0, 0x2000
	s_addc_u32 s1, s1, 0
	global_store_dwordx4 v250, v[54:57], s[0:1] sc0 sc1
	s_add_u32 s0, s0, 0x2000
	s_addc_u32 s1, s1, 0
	global_store_dwordx4 v250, v[58:61], s[0:1] sc0 sc1
	s_add_u32 s0, s0, 0x2000
	s_addc_u32 s1, s1, 0
	global_store_dwordx4 v250, v[62:65], s[0:1] sc0 sc1
	s_add_u32 s0, s0, 0x2000
	s_addc_u32 s1, s1, 0
	global_store_dwordx4 v250, v[66:69], s[0:1] sc0 sc1
	s_add_u32 s0, s0, 0x2000
	s_addc_u32 s1, s1, 0
	global_store_dwordx4 v250, v[70:73], s[0:1] sc0 sc1
	s_add_u32 s0, s0, 0x2000
	s_addc_u32 s1, s1, 0
	global_store_dwordx4 v250, v[74:77], s[0:1] sc0 sc1
	s_add_u32 s0, s0, 0x2000
	s_addc_u32 s1, s1, 0
	global_store_dwordx4 v250, v[78:81], s[0:1] sc0 sc1
	s_add_u32 s0, s0, 0x2000
	s_addc_u32 s1, s1, 0
	global_store_dwordx4 v250, v[82:85], s[0:1] sc0 sc1
	s_add_u32 s0, s0, 0x2000
	s_addc_u32 s1, s1, 0
	global_store_dwordx4 v250, v[86:89], s[0:1] sc0 sc1
	s_add_u32 s0, s0, 0x2000
	s_addc_u32 s1, s1, 0
	global_store_dwordx4 v250, v[90:93], s[0:1] sc0 sc1
	s_add_u32 s0, s0, 0x2000
	s_addc_u32 s1, s1, 0
	global_store_dwordx4 v250, v[94:97], s[0:1] sc0 sc1
	s_add_u32 s0, s0, 0x2000
	s_addc_u32 s1, s1, 0
	global_store_dwordx4 v250, v[98:101], s[0:1] sc0 sc1
	s_add_u32 s0, s0, 0x2000
	s_addc_u32 s1, s1, 0
	global_store_dwordx4 v250, v[102:105], s[0:1] sc0 sc1
	s_add_u32 s0, s0, 0x2000
	s_addc_u32 s1, s1, 0
	global_store_dwordx4 v250, v[106:109], s[0:1] sc0 sc1
	s_add_u32 s0, s0, 0x2000
	s_addc_u32 s1, s1, 0
	global_store_dwordx4 v250, v[110:113], s[0:1] sc0 sc1
	s_add_u32 s0, s0, 0x2000
	s_addc_u32 s1, s1, 0
	global_store_dwordx4 v250, v[114:117], s[0:1] sc0 sc1
	s_add_u32 s0, s0, 0x2000
	s_addc_u32 s1, s1, 0
	global_store_dwordx4 v250, v[118:121], s[0:1] sc0 sc1
	s_add_u32 s0, s0, 0x2000
	s_addc_u32 s1, s1, 0
	global_store_dwordx4 v250, v[122:125], s[0:1] sc0 sc1
	s_add_u32 s0, s0, 0x2000
	s_addc_u32 s1, s1, 0
	global_store_dwordx4 v250, v[126:129], s[0:1] sc0 sc1
	s_add_u32 s0, s0, 0x2000
	s_addc_u32 s1, s1, 0
	s_waitcnt vmcnt(0)
	s_barrier
	s_lshl_b32 s8, s9, 2
	s_sub_u32 s0, s92, 0x11301700
	s_subb_u32 s1, s93, 0
	s_add_u32 s0, s0, s8
	s_addc_u32 s1, s1, 0
	v_cmp_eq_u32_e32 vcc, 0, v192
	s_and_saveexec_b64 s[98:99], vcc
	s_cbranch_execz .Lq8_t0done
	buffer_wbl2 sc1
	s_waitcnt vmcnt(0)
	v_mov_b32_e32 v251, 1
	v_mov_b32_e32 v252, 0
	global_atomic_add v251, v252, v251, s[0:1] sc0
	s_waitcnt vmcnt(0)
	buffer_inv sc1
	s_waitcnt vmcnt(0)
	v_mov_b32_e32 v252, 0x20400
	ds_write_b32 v252, v251
	s_waitcnt lgkmcnt(0)
.Lq8_t0done:
	s_or_b64 exec, exec, s[98:99]
	s_barrier
	v_mov_b32_e32 v252, 0x20400
	ds_read_b32 v251, v252
	s_waitcnt lgkmcnt(0)
	v_readfirstlane_b32 s8, v251
	s_nop 3
	s_lshl_b32 s0, 1, s6
	s_sub_u32 s0, s0, 1
	s_and_b32 s8, s8, s0
	s_cmp_eq_u32 s8, s0
	s_cbranch_scc1 .Lq8_last
	s_movk_i32 s95, 0xc00
	s_movk_i32 s33, 0x5000
	v_readlane_b32 s44, v254, 63
	s_movk_i32 s4, 0x2c00
	s_branch .Lq8_epi_end
; template <class Epi, class SchedT>
; DI void gemm_phase(LAS unsigned char* lds, const Gemm g, const SchedT& S, const Epi& E) {
;     ...
;         { int fr2 = fr, fq2 = fq, wr2 = wr, wc2 = wc; asm volatile("" : "+v"(fr2), "+v"(fq2), "+s"(wr2), "+s"(wc2));
;           E(acc, cur, wr2, wc2, fr2, fq2); }
.Lq8_last:
	s_lshl_b32 s8, s7, 18
	s_sub_u32 s0, s92, 0x4600000
	s_subb_u32 s1, s93, 0
	s_add_u32 s0, s0, s8
	s_addc_u32 s1, s1, 0
	global_load_dwordx4 v[2:5], v250, s[0:1]
	s_add_u32 s0, s0, 0x2000
	s_addc_u32 s1, s1, 0
	global_load_dwordx4 v[6:9], v250, s[0:1]
	s_add_u32 s0, s0, 0x2000
	s_addc_u32 s1, s1, 0
	global_load_dwordx4 v[10:13], v250, s[0:1]
	s_add_u32 s0, s0, 0x2000
	s_addc_u32 s1, s1, 0
	global_load_dwordx4 v[14:17], v250, s[0:1]
	s_add_u32 s0, s0, 0x2000
	s_addc_u32 s1, s1, 0
	global_load_dwordx4 v[18:21], v250, s[0:1]
	s_add_u32 s0, s0, 0x2000
	s_addc_u32 s1, s1, 0
	global_load_dwordx4 v[22:25], v250, s[0:1]
	s_add_u32 s0, s0, 0x2000
	s_addc_u32 s1, s1, 0
	global_load_dwordx4 v[26:29], v250, s[0:1]
	s_add_u32 s0, s0, 0x2000
	s_addc_u32 s1, s1, 0
	global_load_dwordx4 v[30:33], v250, s[0:1]
	s_add_u32 s0, s0, 0x2000
	s_addc_u32 s1, s1, 0
	global_load_dwordx4 v[34:37], v250, s[0:1]
	s_add_u32 s0, s0, 0x2000
	s_addc_u32 s1, s1, 0
	global_load_dwordx4 v[38:41], v250, s[0:1]
	s_add_u32 s0, s0, 0x2000
	s_addc_u32 s1, s1, 0
	global_load_dwordx4 v[42:45], v250, s[0:1]
	s_add_u32 s0, s0, 0x2000
	s_addc_u32 s1, s1, 0
	global_load_dwordx4 v[46:49], v250, s[0:1]
	s_add_u32 s0, s0, 0x2000
	s_addc_u32 s1, s1, 0
	global_load_dwordx4 v[50:53], v250, s[0:1]
	s_add_u32 s0, s0, 0x2000
	s_addc_u32 s1, s1, 0
	global_load_dwordx4 v[54:57], v250, s[0:1]
	s_add_u32 s0, s0, 0x2000
	s_addc_u32 s1, s1, 0
	global_load_dwordx4 v[58:61], v250, s[0:1]
	s_add_u32 s0, s0, 0x2000
	s_addc_u32 s1, s1, 0
	global_load_dwordx4 v[62:65], v250, s[0:1]
	s_add_u32 s0, s0, 0x2000
	s_addc_u32 s1, s1, 0
	global_load_dwordx4 v[66:69], v250, s[0:1]
	s_add_u32 s0, s0, 0x2000
	s_addc_u32 s1, s1, 0
	global_load_dwordx4 v[70:73], v250, s[0:1]
	s_add_u32 s0, s0, 0x2000
	s_addc_u32 s1, s1, 0
	global_load_dwordx4 v[74:77], v250, s[0:1]
	s_add_u32 s0, s0, 0x2000
	s_addc_u32 s1, s1, 0
	global_load_dwordx4 v[78:81], v250, s[0:1]
	s_add_u32 s0, s0, 0x2000
	s_addc_u32 s1, s1, 0
	global_load_dwordx4 v[82:85], v250, s[0:1]
	s_add_u32 s0, s0, 0x2000
	s_addc_u32 s1, s1, 0
	global_load_dwordx4 v[86:89], v250, s[0:1]
	s_add_u32 s0, s0, 0x2000
	s_addc_u32 s1, s1, 0
	global_load_dwordx4 v[90:93], v250, s[0:1]
	s_add_u32 s0, s0, 0x2000
	s_addc_u32 s1, s1, 0
	global_load_dwordx4 v[94:97], v250, s[0:1]
	s_add_u32 s0, s0, 0x2000
	s_addc_u32 s1, s1, 0
	global_load_dwordx4 v[98:101], v250, s[0:1]
	s_add_u32 s0, s0, 0x2000
	s_addc_u32 s1, s1, 0
	global_load_dwordx4 v[102:105], v250, s[0:1]
	s_add_u32 s0, s0, 0x2000
	s_addc_u32 s1, s1, 0
	global_load_dwordx4 v[106:109], v250, s[0:1]
	s_add_u32 s0, s0, 0x2000
	s_addc_u32 s1, s1, 0
	global_load_dwordx4 v[110:113], v250, s[0:1]
	s_add_u32 s0, s0, 0x2000
	s_addc_u32 s1, s1, 0
	global_load_dwordx4 v[114:117], v250, s[0:1]
	s_add_u32 s0, s0, 0x2000
	s_addc_u32 s1, s1, 0
	global_load_dwordx4 v[118:121], v250, s[0:1]
	s_add_u32 s0, s0, 0x2000
	s_addc_u32 s1, s1, 0
	global_load_dwordx4 v[122:125], v250, s[0:1]
	s_add_u32 s0, s0, 0x2000
	s_addc_u32 s1, s1, 0
	global_load_dwordx4 v[126:129], v250, s[0:1]
	s_add_u32 s0, s0, 0x2000
	s_addc_u32 s1, s1, 0
	s_waitcnt vmcnt(0)
	global_load_dwordx4 v[218:221], v250, s[0:1]
	s_add_u32 s0, s0, 0x2000
	s_addc_u32 s1, s1, 0
	global_load_dwordx4 v[222:225], v250, s[0:1]
	s_add_u32 s0, s0, 0x2000
	s_addc_u32 s1, s1, 0
	global_load_dwordx4 v[226:229], v250, s[0:1]
	s_add_u32 s0, s0, 0x2000
	s_addc_u32 s1, s1, 0
	global_load_dwordx4 v[230:233], v250, s[0:1]
	s_add_u32 s0, s0, 0x2000
	s_addc_u32 s1, s1, 0
	global_load_dwordx4 v[234:237], v250, s[0:1]
	s_add_u32 s0, s0, 0x2000
	s_addc_u32 s1, s1, 0
	global_load_dwordx4 v[238:241], v250, s[0:1]
	s_add_u32 s0, s0, 0x2000
	s_addc_u32 s1, s1, 0
	global_load_dwordx4 v[242:245], v250, s[0:1]
	s_add_u32 s0, s0, 0x2000
	s_addc_u32 s1, s1, 0
	global_load_dwordx4 v[246:249], v250, s[0:1]
	s_add_u32 s0, s0, 0x2000
	s_addc_u32 s1, s1, 0
	s_waitcnt vmcnt(0)
	v_pk_add_f32 v[2:3], v[2:3], v[218:219]
	v_pk_add_f32 v[4:5], v[4:5], v[220:221]
	v_pk_add_f32 v[6:7], v[6:7], v[222:223]
	v_pk_add_f32 v[8:9], v[8:9], v[224:225]
	v_pk_add_f32 v[10:11], v[10:11], v[226:227]
	v_pk_add_f32 v[12:13], v[12:13], v[228:229]
	v_pk_add_f32 v[14:15], v[14:15], v[230:231]
	v_pk_add_f32 v[16:17], v[16:17], v[232:233]
	v_pk_add_f32 v[18:19], v[18:19], v[234:235]
	v_pk_add_f32 v[20:21], v[20:21], v[236:237]
	v_pk_add_f32 v[22:23], v[22:23], v[238:239]
	v_pk_add_f32 v[24:25], v[24:25], v[240:241]
	v_pk_add_f32 v[26:27], v[26:27], v[242:243]
	v_pk_add_f32 v[28:29], v[28:29], v[244:245]
	v_pk_add_f32 v[30:31], v[30:31], v[246:247]
	v_pk_add_f32 v[32:33], v[32:33], v[248:249]
	global_load_dwordx4 v[218:221], v250, s[0:1]
	s_add_u32 s0, s0, 0x2000
	s_addc_u32 s1, s1, 0
	global_load_dwordx4 v[222:225], v250, s[0:1]
	s_add_u32 s0, s0, 0x2000
	s_addc_u32 s1, s1, 0
	global_load_dwordx4 v[226:229], v250, s[0:1]
	s_add_u32 s0, s0, 0x2000
	s_addc_u32 s1, s1, 0
	global_load_dwordx4 v[230:233], v250, s[0:1]
	s_add_u32 s0, s0, 0x2000
	s_addc_u32 s1, s1, 0
	global_load_dwordx4 v[234:237], v250, s[0:1]
	s_add_u32 s0, s0, 0x2000
	s_addc_u32 s1, s1, 0
	global_load_dwordx4 v[238:241], v250, s[0:1]
	s_add_u32 s0, s0, 0x2000
	s_addc_u32 s1, s1, 0
	global_load_dwordx4 v[242:245], v250, s[0:1]
	s_add_u32 s0, s0, 0x2000
	s_addc_u32 s1, s1, 0
	global_load_dwordx4 v[246:249], v250, s[0:1]
	s_add_u32 s0, s0, 0x2000
	s_addc_u32 s1, s1, 0
	s_waitcnt vmcnt(0)
; template <class Epi, class SchedT>
; DI void gemm_phase(LAS unsigned char* lds, const Gemm g, const SchedT& S, const Epi& E) {
;     ...
;         { int fr2 = fr, fq2 = fq, wr2 = wr, wc2 = wc; asm volatile("" : "+v"(fr2), "+v"(fq2), "+s"(wr2), "+s"(wc2));
;           E(acc, cur, wr2, wc2, fr2, fq2); }
	v_pk_add_f32 v[34:35], v[34:35], v[218:219]
	v_pk_add_f32 v[36:37], v[36:37], v[220:221]
	v_pk_add_f32 v[38:39], v[38:39], v[222:223]
	v_pk_add_f32 v[40:41], v[40:41], v[224:225]
	v_pk_add_f32 v[42:43], v[42:43], v[226:227]
	v_pk_add_f32 v[44:45], v[44:45], v[228:229]
	v_pk_add_f32 v[46:47], v[46:47], v[230:231]
	v_pk_add_f32 v[48:49], v[48:49], v[232:233]
	v_pk_add_f32 v[50:51], v[50:51], v[234:235]
	v_pk_add_f32 v[52:53], v[52:53], v[236:237]
	v_pk_add_f32 v[54:55], v[54:55], v[238:239]
	v_pk_add_f32 v[56:57], v[56:57], v[240:241]
	v_pk_add_f32 v[58:59], v[58:59], v[242:243]
	v_pk_add_f32 v[60:61], v[60:61], v[244:245]
	v_pk_add_f32 v[62:63], v[62:63], v[246:247]
	v_pk_add_f32 v[64:65], v[64:65], v[248:249]
	global_load_dwordx4 v[218:221], v250, s[0:1]
	s_add_u32 s0, s0, 0x2000
	s_addc_u32 s1, s1, 0
	global_load_dwordx4 v[222:225], v250, s[0:1]
	s_add_u32 s0, s0, 0x2000
	s_addc_u32 s1, s1, 0
	global_load_dwordx4 v[226:229], v250, s[0:1]
	s_add_u32 s0, s0, 0x2000
	s_addc_u32 s1, s1, 0
	global_load_dwordx4 v[230:233], v250, s[0:1]
	s_add_u32 s0, s0, 0x2000
	s_addc_u32 s1, s1, 0
	global_load_dwordx4 v[234:237], v250, s[0:1]
	s_add_u32 s0, s0, 0x2000
	s_addc_u32 s1, s1, 0
	global_load_dwordx4 v[238:241], v250, s[0:1]
	s_add_u32 s0, s0, 0x2000
	s_addc_u32 s1, s1, 0
	global_load_dwordx4 v[242:245], v250, s[0:1]
	s_add_u32 s0, s0, 0x2000
	s_addc_u32 s1, s1, 0
	global_load_dwordx4 v[246:249], v250, s[0:1]
	s_add_u32 s0, s0, 0x2000
	s_addc_u32 s1, s1, 0
	s_waitcnt vmcnt(0)
	v_pk_add_f32 v[66:67], v[66:67], v[218:219]
	v_pk_add_f32 v[68:69], v[68:69], v[220:221]
	v_pk_add_f32 v[70:71], v[70:71], v[222:223]
	v_pk_add_f32 v[72:73], v[72:73], v[224:225]
	v_pk_add_f32 v[74:75], v[74:75], v[226:227]
	v_pk_add_f32 v[76:77], v[76:77], v[228:229]
	v_pk_add_f32 v[78:79], v[78:79], v[230:231]
	v_pk_add_f32 v[80:81], v[80:81], v[232:233]
	v_pk_add_f32 v[82:83], v[82:83], v[234:235]
	v_pk_add_f32 v[84:85], v[84:85], v[236:237]
	v_pk_add_f32 v[86:87], v[86:87], v[238:239]
	v_pk_add_f32 v[88:89], v[88:89], v[240:241]
	v_pk_add_f32 v[90:91], v[90:91], v[242:243]
	v_pk_add_f32 v[92:93], v[92:93], v[244:245]
	v_pk_add_f32 v[94:95], v[94:95], v[246:247]
	v_pk_add_f32 v[96:97], v[96:97], v[248:249]
	global_load_dwordx4 v[218:221], v250, s[0:1]
	s_add_u32 s0, s0, 0x2000
	s_addc_u32 s1, s1, 0
	global_load_dwordx4 v[222:225], v250, s[0:1]
	s_add_u32 s0, s0, 0x2000
	s_addc_u32 s1, s1, 0
	global_load_dwordx4 v[226:229], v250, s[0:1]
	s_add_u32 s0, s0, 0x2000
	s_addc_u32 s1, s1, 0
	global_load_dwordx4 v[230:233], v250, s[0:1]
	s_add_u32 s0, s0, 0x2000
	s_addc_u32 s1, s1, 0
	global_load_dwordx4 v[234:237], v250, s[0:1]
	s_add_u32 s0, s0, 0x2000
	s_addc_u32 s1, s1, 0
	global_load_dwordx4 v[238:241], v250, s[0:1]
	s_add_u32 s0, s0, 0x2000
	s_addc_u32 s1, s1, 0
	global_load_dwordx4 v[242:245], v250, s[0:1]
	s_add_u32 s0, s0, 0x2000
	s_addc_u32 s1, s1, 0
	global_load_dwordx4 v[246:249], v250, s[0:1]
	s_add_u32 s0, s0, 0x2000
	s_addc_u32 s1, s1, 0
	s_waitcnt vmcnt(0)
	v_pk_add_f32 v[98:99], v[98:99], v[218:219]
	v_pk_add_f32 v[100:101], v[100:101], v[220:221]
	v_pk_add_f32 v[102:103], v[102:103], v[222:223]
	v_pk_add_f32 v[104:105], v[104:105], v[224:225]
	v_pk_add_f32 v[106:107], v[106:107], v[226:227]
	v_pk_add_f32 v[108:109], v[108:109], v[228:229]
	v_pk_add_f32 v[110:111], v[110:111], v[230:231]
	v_pk_add_f32 v[112:113], v[112:113], v[232:233]
	v_pk_add_f32 v[114:115], v[114:115], v[234:235]
	v_pk_add_f32 v[116:117], v[116:117], v[236:237]
	v_pk_add_f32 v[118:119], v[118:119], v[238:239]
	v_pk_add_f32 v[120:121], v[120:121], v[240:241]
	v_pk_add_f32 v[122:123], v[122:123], v[242:243]
	v_pk_add_f32 v[124:125], v[124:125], v[244:245]
	v_pk_add_f32 v[126:127], v[126:127], v[246:247]
	v_pk_add_f32 v[128:129], v[128:129], v[248:249]
	s_cmp_eq_u32 s6, 1
	s_cbranch_scc1 .Lq8_epi_normal
	global_load_dwordx4 v[218:221], v250, s[0:1]
	s_add_u32 s0, s0, 0x2000
	s_addc_u32 s1, s1, 0
	global_load_dwordx4 v[222:225], v250, s[0:1]
	s_add_u32 s0, s0, 0x2000
	s_addc_u32 s1, s1, 0
	global_load_dwordx4 v[226:229], v250, s[0:1]
	s_add_u32 s0, s0, 0x2000
	s_addc_u32 s1, s1, 0
	global_load_dwordx4 v[230:233], v250, s[0:1]
	s_add_u32 s0, s0, 0x2000
	s_addc_u32 s1, s1, 0
	global_load_dwordx4 v[234:237], v250, s[0:1]
	s_add_u32 s0, s0, 0x2000
	s_addc_u32 s1, s1, 0
	global_load_dwordx4 v[238:241], v250, s[0:1]
	s_add_u32 s0, s0, 0x2000
	s_addc_u32 s1, s1, 0
	global_load_dwordx4 v[242:245], v250, s[0:1]
	s_add_u32 s0, s0, 0x2000
	s_addc_u32 s1, s1, 0
	global_load_dwordx4 v[246:249], v250, s[0:1]
	s_add_u32 s0, s0, 0x2000
	s_addc_u32 s1, s1, 0
	s_waitcnt vmcnt(0)
	v_pk_add_f32 v[2:3], v[2:3], v[218:219]
	v_pk_add_f32 v[4:5], v[4:5], v[220:221]
	v_pk_add_f32 v[6:7], v[6:7], v[222:223]
	v_pk_add_f32 v[8:9], v[8:9], v[224:225]
	v_pk_add_f32 v[10:11], v[10:11], v[226:227]
	v_pk_add_f32 v[12:13], v[12:13], v[228:229]
	v_pk_add_f32 v[14:15], v[14:15], v[230:231]
	v_pk_add_f32 v[16:17], v[16:17], v[232:233]
	v_pk_add_f32 v[18:19], v[18:19], v[234:235]
	v_pk_add_f32 v[20:21], v[20:21], v[236:237]
	v_pk_add_f32 v[22:23], v[22:23], v[238:239]
	v_pk_add_f32 v[24:25], v[24:25], v[240:241]
	v_pk_add_f32 v[26:27], v[26:27], v[242:243]
	v_pk_add_f32 v[28:29], v[28:29], v[244:245]
	v_pk_add_f32 v[30:31], v[30:31], v[246:247]
	v_pk_add_f32 v[32:33], v[32:33], v[248:249]
	global_load_dwordx4 v[218:221], v250, s[0:1]
	s_add_u32 s0, s0, 0x2000
	s_addc_u32 s1, s1, 0
	global_load_dwordx4 v[222:225], v250, s[0:1]
	s_add_u32 s0, s0, 0x2000
	s_addc_u32 s1, s1, 0
	global_load_dwordx4 v[226:229], v250, s[0:1]
	s_add_u32 s0, s0, 0x2000
	s_addc_u32 s1, s1, 0
	global_load_dwordx4 v[230:233], v250, s[0:1]
	s_add_u32 s0, s0, 0x2000
	s_addc_u32 s1, s1, 0
	global_load_dwordx4 v[234:237], v250, s[0:1]
	s_add_u32 s0, s0, 0x2000
	s_addc_u32 s1, s1, 0
	global_load_dwordx4 v[238:241], v250, s[0:1]
	s_add_u32 s0, s0, 0x2000
	s_addc_u32 s1, s1, 0
	global_load_dwordx4 v[242:245], v250, s[0:1]
	s_add_u32 s0, s0, 0x2000
	s_addc_u32 s1, s1, 0
	global_load_dwordx4 v[246:249], v250, s[0:1]
	s_add_u32 s0, s0, 0x2000
	s_addc_u32 s1, s1, 0
	s_waitcnt vmcnt(0)
; template <class Epi, class SchedT>
; DI void gemm_phase(LAS unsigned char* lds, const Gemm g, const SchedT& S, const Epi& E) {
;     ...
;         { int fr2 = fr, fq2 = fq, wr2 = wr, wc2 = wc; asm volatile("" : "+v"(fr2), "+v"(fq2), "+s"(wr2), "+s"(wc2));
;           E(acc, cur, wr2, wc2, fr2, fq2); }
	v_pk_add_f32 v[34:35], v[34:35], v[218:219]
	v_pk_add_f32 v[36:37], v[36:37], v[220:221]
	v_pk_add_f32 v[38:39], v[38:39], v[222:223]
	v_pk_add_f32 v[40:41], v[40:41], v[224:225]
	v_pk_add_f32 v[42:43], v[42:43], v[226:227]
	v_pk_add_f32 v[44:45], v[44:45], v[228:229]
	v_pk_add_f32 v[46:47], v[46:47], v[230:231]
	v_pk_add_f32 v[48:49], v[48:49], v[232:233]
	v_pk_add_f32 v[50:51], v[50:51], v[234:235]
	v_pk_add_f32 v[52:53], v[52:53], v[236:237]
	v_pk_add_f32 v[54:55], v[54:55], v[238:239]
	v_pk_add_f32 v[56:57], v[56:57], v[240:241]
	v_pk_add_f32 v[58:59], v[58:59], v[242:243]
	v_pk_add_f32 v[60:61], v[60:61], v[244:245]
	v_pk_add_f32 v[62:63], v[62:63], v[246:247]
	v_pk_add_f32 v[64:65], v[64:65], v[248:249]
	global_load_dwordx4 v[218:221], v250, s[0:1]
	s_add_u32 s0, s0, 0x2000
	s_addc_u32 s1, s1, 0
	global_load_dwordx4 v[222:225], v250, s[0:1]
	s_add_u32 s0, s0, 0x2000
	s_addc_u32 s1, s1, 0
	global_load_dwordx4 v[226:229], v250, s[0:1]
	s_add_u32 s0, s0, 0x2000
	s_addc_u32 s1, s1, 0
	global_load_dwordx4 v[230:233], v250, s[0:1]
	s_add_u32 s0, s0, 0x2000
	s_addc_u32 s1, s1, 0
	global_load_dwordx4 v[234:237], v250, s[0:1]
	s_add_u32 s0, s0, 0x2000
	s_addc_u32 s1, s1, 0
	global_load_dwordx4 v[238:241], v250, s[0:1]
	s_add_u32 s0, s0, 0x2000
	s_addc_u32 s1, s1, 0
	global_load_dwordx4 v[242:245], v250, s[0:1]
	s_add_u32 s0, s0, 0x2000
	s_addc_u32 s1, s1, 0
	global_load_dwordx4 v[246:249], v250, s[0:1]
	s_add_u32 s0, s0, 0x2000
	s_addc_u32 s1, s1, 0
	s_waitcnt vmcnt(0)
	v_pk_add_f32 v[66:67], v[66:67], v[218:219]
	v_pk_add_f32 v[68:69], v[68:69], v[220:221]
	v_pk_add_f32 v[70:71], v[70:71], v[222:223]
	v_pk_add_f32 v[72:73], v[72:73], v[224:225]
	v_pk_add_f32 v[74:75], v[74:75], v[226:227]
	v_pk_add_f32 v[76:77], v[76:77], v[228:229]
	v_pk_add_f32 v[78:79], v[78:79], v[230:231]
	v_pk_add_f32 v[80:81], v[80:81], v[232:233]
	v_pk_add_f32 v[82:83], v[82:83], v[234:235]
	v_pk_add_f32 v[84:85], v[84:85], v[236:237]
	v_pk_add_f32 v[86:87], v[86:87], v[238:239]
	v_pk_add_f32 v[88:89], v[88:89], v[240:241]
	v_pk_add_f32 v[90:91], v[90:91], v[242:243]
	v_pk_add_f32 v[92:93], v[92:93], v[244:245]
	v_pk_add_f32 v[94:95], v[94:95], v[246:247]
	v_pk_add_f32 v[96:97], v[96:97], v[248:249]
	global_load_dwordx4 v[218:221], v250, s[0:1]
	s_add_u32 s0, s0, 0x2000
	s_addc_u32 s1, s1, 0
	global_load_dwordx4 v[222:225], v250, s[0:1]
	s_add_u32 s0, s0, 0x2000
	s_addc_u32 s1, s1, 0
	global_load_dwordx4 v[226:229], v250, s[0:1]
	s_add_u32 s0, s0, 0x2000
	s_addc_u32 s1, s1, 0
	global_load_dwordx4 v[230:233], v250, s[0:1]
	s_add_u32 s0, s0, 0x2000
	s_addc_u32 s1, s1, 0
	global_load_dwordx4 v[234:237], v250, s[0:1]
	s_add_u32 s0, s0, 0x2000
	s_addc_u32 s1, s1, 0
	global_load_dwordx4 v[238:241], v250, s[0:1]
	s_add_u32 s0, s0, 0x2000
	s_addc_u32 s1, s1, 0
	global_load_dwordx4 v[242:245], v250, s[0:1]
	s_add_u32 s0, s0, 0x2000
	s_addc_u32 s1, s1, 0
	global_load_dwordx4 v[246:249], v250, s[0:1]
	s_add_u32 s0, s0, 0x2000
	s_addc_u32 s1, s1, 0
	s_waitcnt vmcnt(0)
	v_pk_add_f32 v[98:99], v[98:99], v[218:219]
	v_pk_add_f32 v[100:101], v[100:101], v[220:221]
	v_pk_add_f32 v[102:103], v[102:103], v[222:223]
	v_pk_add_f32 v[104:105], v[104:105], v[224:225]
	v_pk_add_f32 v[106:107], v[106:107], v[226:227]
	v_pk_add_f32 v[108:109], v[108:109], v[228:229]
	v_pk_add_f32 v[110:111], v[110:111], v[230:231]
	v_pk_add_f32 v[112:113], v[112:113], v[232:233]
	v_pk_add_f32 v[114:115], v[114:115], v[234:235]
	v_pk_add_f32 v[116:117], v[116:117], v[236:237]
	v_pk_add_f32 v[118:119], v[118:119], v[238:239]
	v_pk_add_f32 v[120:121], v[120:121], v[240:241]
	v_pk_add_f32 v[122:123], v[122:123], v[242:243]
	v_pk_add_f32 v[124:125], v[124:125], v[244:245]
	v_pk_add_f32 v[126:127], v[126:127], v[246:247]
	v_pk_add_f32 v[128:129], v[128:129], v[248:249]
	global_load_dwordx4 v[218:221], v250, s[0:1]
	s_add_u32 s0, s0, 0x2000
	s_addc_u32 s1, s1, 0
	global_load_dwordx4 v[222:225], v250, s[0:1]
	s_add_u32 s0, s0, 0x2000
	s_addc_u32 s1, s1, 0
	global_load_dwordx4 v[226:229], v250, s[0:1]
	s_add_u32 s0, s0, 0x2000
	s_addc_u32 s1, s1, 0
	global_load_dwordx4 v[230:233], v250, s[0:1]
	s_add_u32 s0, s0, 0x2000
	s_addc_u32 s1, s1, 0
	global_load_dwordx4 v[234:237], v250, s[0:1]
	s_add_u32 s0, s0, 0x2000
	s_addc_u32 s1, s1, 0
	global_load_dwordx4 v[238:241], v250, s[0:1]
	s_add_u32 s0, s0, 0x2000
	s_addc_u32 s1, s1, 0
	global_load_dwordx4 v[242:245], v250, s[0:1]
	s_add_u32 s0, s0, 0x2000
	s_addc_u32 s1, s1, 0
	global_load_dwordx4 v[246:249], v250, s[0:1]
	s_add_u32 s0, s0, 0x2000
	s_addc_u32 s1, s1, 0
	s_waitcnt vmcnt(0)
	v_pk_add_f32 v[2:3], v[2:3], v[218:219]
	v_pk_add_f32 v[4:5], v[4:5], v[220:221]
	v_pk_add_f32 v[6:7], v[6:7], v[222:223]
	v_pk_add_f32 v[8:9], v[8:9], v[224:225]
	v_pk_add_f32 v[10:11], v[10:11], v[226:227]
	v_pk_add_f32 v[12:13], v[12:13], v[228:229]
	v_pk_add_f32 v[14:15], v[14:15], v[230:231]
	v_pk_add_f32 v[16:17], v[16:17], v[232:233]
	v_pk_add_f32 v[18:19], v[18:19], v[234:235]
	v_pk_add_f32 v[20:21], v[20:21], v[236:237]
	v_pk_add_f32 v[22:23], v[22:23], v[238:239]
	v_pk_add_f32 v[24:25], v[24:25], v[240:241]
	v_pk_add_f32 v[26:27], v[26:27], v[242:243]
	v_pk_add_f32 v[28:29], v[28:29], v[244:245]
	v_pk_add_f32 v[30:31], v[30:31], v[246:247]
	v_pk_add_f32 v[32:33], v[32:33], v[248:249]
	global_load_dwordx4 v[218:221], v250, s[0:1]
	s_add_u32 s0, s0, 0x2000
	s_addc_u32 s1, s1, 0
	global_load_dwordx4 v[222:225], v250, s[0:1]
	s_add_u32 s0, s0, 0x2000
	s_addc_u32 s1, s1, 0
	global_load_dwordx4 v[226:229], v250, s[0:1]
	s_add_u32 s0, s0, 0x2000
	s_addc_u32 s1, s1, 0
	global_load_dwordx4 v[230:233], v250, s[0:1]
	s_add_u32 s0, s0, 0x2000
	s_addc_u32 s1, s1, 0
	global_load_dwordx4 v[234:237], v250, s[0:1]
	s_add_u32 s0, s0, 0x2000
	s_addc_u32 s1, s1, 0
	global_load_dwordx4 v[238:241], v250, s[0:1]
	s_add_u32 s0, s0, 0x2000
	s_addc_u32 s1, s1, 0
	global_load_dwordx4 v[242:245], v250, s[0:1]
	s_add_u32 s0, s0, 0x2000
	s_addc_u32 s1, s1, 0
	global_load_dwordx4 v[246:249], v250, s[0:1]
	s_add_u32 s0, s0, 0x2000
	s_addc_u32 s1, s1, 0
	s_waitcnt vmcnt(0)
;     DI void operator()(AccRef acc, const Unit& u, int wr, int wc, int fr, int fq) const {
; #pragma unroll
;         for (int n = 0; n < 2; ++n) {
;             const int cg_ = 128 * u.pn + 32 * wc + 8 * fq + 4 * n;
;             f32x4 o[2][4];
; #pragma unroll
;             for (int bj = 0; bj < 2; ++bj) {
;                 const f32x4 w0 = *(const f32x4*)(cw + bj * DFF + cg_), w1 = *(const f32x4*)(cw + (size_t)2 * DFF + bj * DFF + cg_),
;                             w2 = *(const f32x4*)(cw + (size_t)4 * DFF + bj * DFF + cg_), wb = *(const f32x4*)(cb + bj * DFF + cg_);
; #pragma unroll
;                 for (int ai = 0; ai < 2; ++ai) {
;                     const int tok0 = 252 * u.pm - 1 + 126 * wr + 64 * ai;
; #pragma unroll
;                     for (int m = 0; m < 4; ++m) {
;                         const int tok = tok0 + 16 * m + fr; const int msk = tok < ML ? 4095 : 255;
;                         const bool hu = (tok & msk) != 0, hd = ((tok + 1) & msk) != 0;
;                         f32x4 r = acc[ai][bj][m][n] * w1 + wb;
;                         f32x4 w0m, w2m;
; #pragma unroll
;                         for (int j = 0; j < 4; ++j) { w0m[j] = hu ? w0[j] : 0.f; w2m[j] = hd ? w2[j] : 0.f; }
	v_pk_add_f32 v[34:35], v[34:35], v[218:219]
	v_pk_add_f32 v[36:37], v[36:37], v[220:221]
	v_pk_add_f32 v[38:39], v[38:39], v[222:223]
	v_pk_add_f32 v[40:41], v[40:41], v[224:225]
	v_pk_add_f32 v[42:43], v[42:43], v[226:227]
	v_pk_add_f32 v[44:45], v[44:45], v[228:229]
	v_pk_add_f32 v[46:47], v[46:47], v[230:231]
	v_pk_add_f32 v[48:49], v[48:49], v[232:233]
	v_pk_add_f32 v[50:51], v[50:51], v[234:235]
	v_pk_add_f32 v[52:53], v[52:53], v[236:237]
	v_pk_add_f32 v[54:55], v[54:55], v[238:239]
	v_pk_add_f32 v[56:57], v[56:57], v[240:241]
	v_pk_add_f32 v[58:59], v[58:59], v[242:243]
	v_pk_add_f32 v[60:61], v[60:61], v[244:245]
	v_pk_add_f32 v[62:63], v[62:63], v[246:247]
	v_pk_add_f32 v[64:65], v[64:65], v[248:249]
	global_load_dwordx4 v[218:221], v250, s[0:1]
	s_add_u32 s0, s0, 0x2000
	s_addc_u32 s1, s1, 0
	global_load_dwordx4 v[222:225], v250, s[0:1]
	s_add_u32 s0, s0, 0x2000
	s_addc_u32 s1, s1, 0
	global_load_dwordx4 v[226:229], v250, s[0:1]
	s_add_u32 s0, s0, 0x2000
	s_addc_u32 s1, s1, 0
	global_load_dwordx4 v[230:233], v250, s[0:1]
	s_add_u32 s0, s0, 0x2000
	s_addc_u32 s1, s1, 0
	global_load_dwordx4 v[234:237], v250, s[0:1]
	s_add_u32 s0, s0, 0x2000
	s_addc_u32 s1, s1, 0
	global_load_dwordx4 v[238:241], v250, s[0:1]
	s_add_u32 s0, s0, 0x2000
	s_addc_u32 s1, s1, 0
	global_load_dwordx4 v[242:245], v250, s[0:1]
	s_add_u32 s0, s0, 0x2000
	s_addc_u32 s1, s1, 0
	global_load_dwordx4 v[246:249], v250, s[0:1]
	s_add_u32 s0, s0, 0x2000
	s_addc_u32 s1, s1, 0
	s_waitcnt vmcnt(0)
	v_pk_add_f32 v[66:67], v[66:67], v[218:219]
	v_pk_add_f32 v[68:69], v[68:69], v[220:221]
	v_pk_add_f32 v[70:71], v[70:71], v[222:223]
	v_pk_add_f32 v[72:73], v[72:73], v[224:225]
	v_pk_add_f32 v[74:75], v[74:75], v[226:227]
	v_pk_add_f32 v[76:77], v[76:77], v[228:229]
	v_pk_add_f32 v[78:79], v[78:79], v[230:231]
	v_pk_add_f32 v[80:81], v[80:81], v[232:233]
	v_pk_add_f32 v[82:83], v[82:83], v[234:235]
	v_pk_add_f32 v[84:85], v[84:85], v[236:237]
	v_pk_add_f32 v[86:87], v[86:87], v[238:239]
	v_pk_add_f32 v[88:89], v[88:89], v[240:241]
	v_pk_add_f32 v[90:91], v[90:91], v[242:243]
	v_pk_add_f32 v[92:93], v[92:93], v[244:245]
	v_pk_add_f32 v[94:95], v[94:95], v[246:247]
	v_pk_add_f32 v[96:97], v[96:97], v[248:249]
	global_load_dwordx4 v[218:221], v250, s[0:1]
	s_add_u32 s0, s0, 0x2000
	s_addc_u32 s1, s1, 0
	global_load_dwordx4 v[222:225], v250, s[0:1]
	s_add_u32 s0, s0, 0x2000
	s_addc_u32 s1, s1, 0
	global_load_dwordx4 v[226:229], v250, s[0:1]
	s_add_u32 s0, s0, 0x2000
	s_addc_u32 s1, s1, 0
	global_load_dwordx4 v[230:233], v250, s[0:1]
	s_add_u32 s0, s0, 0x2000
	s_addc_u32 s1, s1, 0
	global_load_dwordx4 v[234:237], v250, s[0:1]
	s_add_u32 s0, s0, 0x2000
	s_addc_u32 s1, s1, 0
	global_load_dwordx4 v[238:241], v250, s[0:1]
	s_add_u32 s0, s0, 0x2000
	s_addc_u32 s1, s1, 0
	global_load_dwordx4 v[242:245], v250, s[0:1]
	s_add_u32 s0, s0, 0x2000
	s_addc_u32 s1, s1, 0
	global_load_dwordx4 v[246:249], v250, s[0:1]
	s_add_u32 s0, s0, 0x2000
	s_addc_u32 s1, s1, 0
	s_waitcnt vmcnt(0)
	v_pk_add_f32 v[98:99], v[98:99], v[218:219]
	v_pk_add_f32 v[100:101], v[100:101], v[220:221]
	v_pk_add_f32 v[102:103], v[102:103], v[222:223]
	v_pk_add_f32 v[104:105], v[104:105], v[224:225]
	v_pk_add_f32 v[106:107], v[106:107], v[226:227]
	v_pk_add_f32 v[108:109], v[108:109], v[228:229]
	v_pk_add_f32 v[110:111], v[110:111], v[230:231]
	v_pk_add_f32 v[112:113], v[112:113], v[232:233]
	v_pk_add_f32 v[114:115], v[114:115], v[234:235]
	v_pk_add_f32 v[116:117], v[116:117], v[236:237]
	v_pk_add_f32 v[118:119], v[118:119], v[238:239]
	v_pk_add_f32 v[120:121], v[120:121], v[240:241]
	v_pk_add_f32 v[122:123], v[122:123], v[242:243]
	v_pk_add_f32 v[124:125], v[124:125], v[244:245]
	v_pk_add_f32 v[126:127], v[126:127], v[246:247]
	v_pk_add_f32 v[128:129], v[128:129], v[248:249]
.Lq8_epi_normal:
	v_mov_b32_e32 v205, v184
	s_mov_b32 s0, s65
	v_mov_b32_e32 v0, v185
	s_mov_b32 s1, s89
	s_lshl_b32 s4, s4, 7
	s_lshl_b32 s1, s1, 5
	s_add_i32 s1, s1, s4
	v_lshl_add_u32 v146, v0, 3, s1
	s_mul_i32 s1, s10, 0xfc
	s_mulk_i32 s0, 0x7e
	v_subrev_co_u32_e64 v206, s[4:5], 1, v205
	s_add_i32 s0, s0, s1
	v_ashrrev_i32_e32 v147, 31, v146
	v_add_u32_e32 v0, s0, v206
	v_lshlrev_b64 v[130:131], 2, v[146:147]
	v_readlane_b32 s0, v255, 0
	v_lshl_add_u64 v[150:151], s[62:63], 0, v[130:131]
	v_readlane_b32 s1, v255, 1
	v_lshl_add_u64 v[174:175], s[84:85], 0, v[130:131]
	v_lshl_add_u64 v[172:173], s[50:51], 0, v[130:131]
	v_lshl_add_u64 v[148:149], s[0:1], 0, v[130:131]
	global_load_dwordx4 v[134:137], v[150:151], off
	global_load_dwordx4 v[130:133], v[174:175], off
	global_load_dwordx4 v[138:141], v[172:173], off
	global_load_dwordx4 v[142:145], v[148:149], off
	s_mov_b64 s[98:99], 0x5000
	v_lshl_add_u64 v[178:179], v[150:151], 0, s[98:99]
	v_lshl_add_u64 v[180:181], v[174:175], 0, s[98:99]
	v_lshl_add_u64 v[182:183], v[172:173], 0, s[98:99]
	v_lshl_add_u64 v[194:195], v[148:149], 0, s[98:99]
	global_load_dwordx4 v[218:221], v[180:181], off offset:2048
	global_load_dwordx4 v[222:225], v[194:195], off offset:2048
	global_load_dwordx4 v[226:229], v[178:179], off offset:2048
	global_load_dwordx4 v[230:233], v[182:183], off offset:2048
	global_load_dwordx4 v[234:237], v[150:151], off offset:16
	global_load_dwordx4 v[238:241], v[174:175], off offset:16
	global_load_dwordx4 v[242:245], v[172:173], off offset:16
	global_load_dwordx4 v[246:249], v[148:149], off offset:16
	global_load_dwordx4 v[250:253], v[178:179], off offset:2064
	global_load_dwordx4 v[208:211], v[180:181], off offset:2064
	global_load_dwordx4 v[212:215], v[182:183], off offset:2064
	global_load_dwordx4 v[196:199], v[194:195], off offset:2064
	v_cmp_gt_i32_e64 s[0:1], s72, v0
	v_mov_b32_e32 v176, 0xff
	v_mov_b32_e32 v177, 0xfff
	v_cndmask_b32_e64 v152, v176, v177, s[0:1]
	v_and_b32_e32 v153, v152, v0
	v_cmp_eq_u32_e64 s[6:7], 0, v153
	v_add_u32_e32 v153, 1, v0
	v_and_b32_e32 v152, v152, v153
	v_add_u32_e32 v188, 16, v0
	v_cmp_eq_u32_e64 s[8:9], 0, v152
	v_cmp_gt_i32_e64 s[0:1], s72, v188
	v_cndmask_b32_e64 v167, v126, v122, s[4:5]
	v_cmp_eq_u32_e32 vcc, 15, v205
	v_add_u32_e32 v189, 32, v0
	v_cndmask_b32_e64 v166, v127, v123, s[4:5]
	v_cndmask_b32_e64 v164, v129, v125, s[4:5]
	v_add_u32_e32 v191, 48, v0
	v_cndmask_b32_e64 v165, v128, v124, s[4:5]
	v_cndmask_b32_e64 v170, v123, v119, s[4:5]
	v_cndmask_b32_e64 v171, v122, v118, s[4:5]
	v_cndmask_b32_e64 v168, v125, v121, s[4:5]
	v_add_u32_e32 v202, 64, v0
	v_cndmask_b32_e64 v169, v124, v120, s[4:5]
	v_add_u32_e32 v204, 0x50, v0
	v_add_u32_e32 v203, 0x60, v0
	v_add_u32_e32 v190, 0x70, v0
	s_movk_i32 s33, 0x5000
	v_readlane_b32 s44, v254, 63
	s_waitcnt vmcnt(12)
;     DI void operator()(AccRef acc, const Unit& u, int wr, int wc, int fr, int fq) const {
;     ...
;                     for (int m = 0; m < 4; ++m) {
;                         const int tok = tok0 + 16 * m + fr; const int msk = tok < ML ? 4095 : 255;
;                         const bool hu = (tok & msk) != 0, hd = ((tok + 1) & msk) != 0;
;                         f32x4 r = acc[ai][bj][m][n] * w1 + wb;
;                         f32x4 w0m, w2m;
; #pragma unroll
;                         for (int j = 0; j < 4; ++j) { w0m[j] = hu ? w0[j] : 0.f; w2m[j] = hd ? w2[j] : 0.f; }
; #pragma unroll
;                         for (int j = 0; j < 4; ++j) {
;                             const float su = ((m > 0 || ai == 1) && fr == 15) ? (m > 0 ? acc[ai][bj][(m + 3) & 3][n][j] : acc[0][bj][3][n][j]) : acc[ai][bj][m][n][j];
;                             const float sd = ((m < 3 || ai == 0) && fr == 0) ? (m < 3 ? acc[ai][bj][(m + 1) & 3][n][j] : acc[1][bj][0][n][j]) : acc[ai][bj][m][n][j];
;                             float rj = r[j];
;                             asm("s_nop 1\n\tv_fmac_f32_dpp %0, %1, %2 row_ror:1 row_mask:0xf bank_mask:0xf" : "+v"(rj) : "v"(su), "v"(w0m[j]));
;                             asm("s_nop 1\n\tv_fmac_f32_dpp %0, %1, %2 row_ror:15 row_mask:0xf bank_mask:0xf" : "+v"(rj) : "v"(sd), "v"(w2m[j]));
;                             r[j] = rj; }
	v_cndmask_b32_e64 v156, v134, 0, s[6:7]
	v_cndmask_b32_e64 v158, v135, 0, s[6:7]
	v_cndmask_b32_e64 v157, v138, 0, s[8:9]
	v_pk_fma_f32 v[154:155], v[126:127], v[130:131], v[142:143]
	v_cndmask_b32_e64 v159, v139, 0, s[8:9]
	s_nop 1
	v_fmac_f32_dpp v154, v126, v156 row_ror:1 row_mask:0xf bank_mask:0xf
	v_cndmask_b32_e64 v156, v176, v177, s[0:1]
	s_nop 1
	v_fmac_f32_dpp v154, v167, v157 row_ror:15 row_mask:0xf bank_mask:0xf
	v_and_b32_e32 v157, v156, v188
	s_nop 1
	v_fmac_f32_dpp v155, v127, v158 row_ror:1 row_mask:0xf bank_mask:0xf
	v_cmp_eq_u32_e64 s[10:11], 0, v157
	v_add_u32_e32 v157, 17, v0
	v_cndmask_b32_e64 v160, v136, 0, s[6:7]
	v_pk_fma_f32 v[152:153], v[128:129], v[132:133], v[144:145]
	s_nop 1
	v_fmac_f32_dpp v155, v166, v159 row_ror:15 row_mask:0xf bank_mask:0xf
	v_and_b32_e32 v156, v156, v157
	v_pk_fma_f32 v[158:159], v[122:123], v[130:131], v[142:143]
	v_cndmask_b32_e32 v126, v122, v126, vcc
	v_cmp_gt_i32_e64 s[0:1], s72, v189
	v_cndmask_b32_e64 v162, v137, 0, s[6:7]
	v_cndmask_b32_e64 v163, v141, 0, s[8:9]
	s_nop 1
	v_fmac_f32_dpp v152, v128, v160 row_ror:1 row_mask:0xf bank_mask:0xf
	s_nop 1
	v_fmac_f32_dpp v153, v129, v162 row_ror:1 row_mask:0xf bank_mask:0xf
	v_cmp_eq_u32_e64 s[12:13], 0, v156
	v_cndmask_b32_e64 v160, v134, 0, s[10:11]
	v_cndmask_b32_e32 v127, v123, v127, vcc
	s_nop 1
	v_fmac_f32_dpp v158, v126, v160 row_ror:1 row_mask:0xf bank_mask:0xf
	v_cndmask_b32_e64 v126, v176, v177, s[0:1]
	s_nop 1
	v_fmac_f32_dpp v153, v164, v163 row_ror:15 row_mask:0xf bank_mask:0xf
	v_cndmask_b32_e64 v162, v135, 0, s[10:11]
	v_cndmask_b32_e64 v163, v139, 0, s[12:13]
	s_nop 1
	v_fmac_f32_dpp v159, v127, v162 row_ror:1 row_mask:0xf bank_mask:0xf
	v_and_b32_e32 v127, v126, v189
	v_pk_fma_f32 v[156:157], v[124:125], v[132:133], v[144:145]
	v_cndmask_b32_e32 v128, v124, v128, vcc
	s_nop 1
	v_fmac_f32_dpp v159, v170, v163 row_ror:15 row_mask:0xf bank_mask:0xf
	v_cmp_eq_u32_e64 s[14:15], 0, v127
	v_add_u32_e32 v127, 33, v0
	v_pk_fma_f32 v[162:163], v[118:119], v[130:131], v[142:143]
	v_cndmask_b32_e32 v122, v118, v122, vcc
	v_cmp_gt_i32_e64 s[0:1], s72, v191
	v_cndmask_b32_e64 v164, v136, 0, s[10:11]
	s_nop 1
	v_fmac_f32_dpp v156, v128, v164 row_ror:1 row_mask:0xf bank_mask:0xf
	v_and_b32_e32 v126, v126, v127
	v_cndmask_b32_e64 v128, v134, 0, s[14:15]
	v_cndmask_b32_e32 v123, v119, v123, vcc
	s_nop 1
	v_fmac_f32_dpp v162, v122, v128 row_ror:1 row_mask:0xf bank_mask:0xf
	v_cndmask_b32_e64 v122, v176, v177, s[0:1]
	v_cndmask_b32_e64 v166, v137, 0, s[10:11]
	v_cndmask_b32_e64 v167, v141, 0, s[12:13]
	v_cndmask_b32_e32 v129, v125, v129, vcc
	s_nop 1
	v_fmac_f32_dpp v157, v129, v166 row_ror:1 row_mask:0xf bank_mask:0xf
	v_cmp_eq_u32_e64 s[16:17], 0, v126
	v_cndmask_b32_e64 v160, v135, 0, s[14:15]
	v_pk_fma_f32 v[126:127], v[120:121], v[132:133], v[144:145]
	s_nop 1
	v_fmac_f32_dpp v163, v123, v160 row_ror:1 row_mask:0xf bank_mask:0xf
	v_and_b32_e32 v123, v122, v191
	v_cndmask_b32_e64 v161, v140, 0, s[8:9]
	s_nop 1
	v_fmac_f32_dpp v157, v168, v167 row_ror:15 row_mask:0xf bank_mask:0xf
	v_cndmask_b32_e64 v166, v137, 0, s[14:15]
	v_cndmask_b32_e64 v167, v141, 0, s[16:17]
	v_cndmask_b32_e32 v125, v121, v125, vcc
	s_nop 1
	v_fmac_f32_dpp v127, v125, v166 row_ror:1 row_mask:0xf bank_mask:0xf
	v_cmp_eq_u32_e64 s[18:19], 0, v123
	v_add_u32_e32 v123, 49, v0
	s_nop 1
	v_fmac_f32_dpp v152, v165, v161 row_ror:15 row_mask:0xf bank_mask:0xf
	v_cndmask_b32_e64 v161, v138, 0, s[12:13]
	s_nop 1
	v_fmac_f32_dpp v158, v171, v161 row_ror:15 row_mask:0xf bank_mask:0xf
	v_cndmask_b32_e64 v168, v121, v117, s[4:5]
	v_cndmask_b32_e64 v171, v118, v114, s[4:5]
	s_nop 1
	v_fmac_f32_dpp v127, v168, v167 row_ror:15 row_mask:0xf bank_mask:0xf
	v_and_b32_e32 v122, v122, v123
	v_pk_fma_f32 v[166:167], v[114:115], v[130:131], v[142:143]
	v_cndmask_b32_e32 v118, v114, v118, vcc
	v_cmp_gt_i32_e64 s[0:1], s72, v202
	v_cndmask_b32_e64 v129, v138, 0, s[16:17]
	v_cndmask_b32_e32 v124, v120, v124, vcc
	v_cndmask_b32_e64 v170, v119, v115, s[4:5]
	v_cmp_eq_u32_e64 s[20:21], 0, v122
	v_cndmask_b32_e64 v122, v134, 0, s[18:19]
	v_cndmask_b32_e32 v119, v115, v119, vcc
	s_nop 1
	v_fmac_f32_dpp v166, v118, v122 row_ror:1 row_mask:0xf bank_mask:0xf
	v_cndmask_b32_e64 v118, v176, v177, s[0:1]
	v_cndmask_b32_e64 v165, v140, 0, s[12:13]
	s_nop 1
	v_fmac_f32_dpp v156, v169, v165 row_ror:15 row_mask:0xf bank_mask:0xf
	v_cndmask_b32_e64 v164, v136, 0, s[14:15]
	v_cndmask_b32_e64 v169, v120, v116, s[4:5]
	s_nop 1
	v_fmac_f32_dpp v162, v171, v129 row_ror:15 row_mask:0xf bank_mask:0xf
	s_nop 1
	v_fmac_f32_dpp v126, v124, v164 row_ror:1 row_mask:0xf bank_mask:0xf
	v_cndmask_b32_e64 v124, v135, 0, s[18:19]
	v_pk_fma_f32 v[128:129], v[116:117], v[132:133], v[144:145]
	s_nop 1
	v_fmac_f32_dpp v167, v119, v124 row_ror:1 row_mask:0xf bank_mask:0xf
	v_and_b32_e32 v119, v118, v202
	v_cndmask_b32_e64 v161, v139, 0, s[16:17]
	v_cndmask_b32_e64 v165, v140, 0, s[16:17]
	s_nop 1
	v_fmac_f32_dpp v126, v169, v165 row_ror:15 row_mask:0xf bank_mask:0xf
	v_cndmask_b32_e64 v160, v136, 0, s[18:19]
	v_cndmask_b32_e64 v164, v137, 0, s[18:19]
	v_cndmask_b32_e32 v121, v117, v121, vcc
	v_cndmask_b32_e32 v120, v116, v120, vcc
	v_cndmask_b32_e64 v168, v117, v113, s[4:5]
	v_cndmask_b32_e64 v169, v116, v112, s[4:5]
	s_nop 1
	v_fmac_f32_dpp v128, v120, v160 row_ror:1 row_mask:0xf bank_mask:0xf
	s_nop 1
	v_fmac_f32_dpp v129, v121, v164 row_ror:1 row_mask:0xf bank_mask:0xf
	v_cmp_eq_u32_e64 s[22:23], 0, v119
	v_add_u32_e32 v119, 0x41, v0
	s_nop 1
	v_fmac_f32_dpp v163, v170, v161 row_ror:15 row_mask:0xf bank_mask:0xf
	v_cndmask_b32_e64 v161, v140, 0, s[20:21]
	v_cndmask_b32_e64 v165, v141, 0, s[20:21]
	v_cndmask_b32_e64 v171, v114, v110, s[4:5]
;     DI void operator()(AccRef acc, const Unit& u, int wr, int wc, int fr, int fq) const {
;     ...
;                     for (int m = 0; m < 4; ++m) {
;                         const int tok = tok0 + 16 * m + fr; const int msk = tok < ML ? 4095 : 255;
;                         const bool hu = (tok & msk) != 0, hd = ((tok + 1) & msk) != 0;
;                         f32x4 r = acc[ai][bj][m][n] * w1 + wb;
;                         f32x4 w0m, w2m;
; #pragma unroll
;                         for (int j = 0; j < 4; ++j) { w0m[j] = hu ? w0[j] : 0.f; w2m[j] = hd ? w2[j] : 0.f; }
; #pragma unroll
;                         for (int j = 0; j < 4; ++j) {
;                             const float su = ((m > 0 || ai == 1) && fr == 15) ? (m > 0 ? acc[ai][bj][(m + 3) & 3][n][j] : acc[0][bj][3][n][j]) : acc[ai][bj][m][n][j];
;                             const float sd = ((m < 3 || ai == 0) && fr == 0) ? (m < 3 ? acc[ai][bj][(m + 1) & 3][n][j] : acc[1][bj][0][n][j]) : acc[ai][bj][m][n][j];
;                             float rj = r[j];
;                             asm("s_nop 1\n\tv_fmac_f32_dpp %0, %1, %2 row_ror:1 row_mask:0xf bank_mask:0xf" : "+v"(rj) : "v"(su), "v"(w0m[j]));
;                             asm("s_nop 1\n\tv_fmac_f32_dpp %0, %1, %2 row_ror:15 row_mask:0xf bank_mask:0xf" : "+v"(rj) : "v"(sd), "v"(w2m[j]));
;                             r[j] = rj; }
	s_nop 1
	v_fmac_f32_dpp v128, v169, v161 row_ror:15 row_mask:0xf bank_mask:0xf
	s_nop 1
	v_fmac_f32_dpp v129, v168, v165 row_ror:15 row_mask:0xf bank_mask:0xf
	v_and_b32_e32 v118, v118, v119
	v_pk_fma_f32 v[168:169], v[110:111], v[130:131], v[142:143]
	v_cndmask_b32_e32 v114, v110, v114, vcc
	v_cmp_gt_i32_e64 s[0:1], s72, v204
	v_cndmask_b32_e64 v170, v115, v111, s[4:5]
	v_cmp_eq_u32_e64 s[24:25], 0, v118
	v_cndmask_b32_e64 v118, v134, 0, s[22:23]
	v_cndmask_b32_e32 v115, v111, v115, vcc
	s_nop 1
	v_fmac_f32_dpp v168, v114, v118 row_ror:1 row_mask:0xf bank_mask:0xf
	v_cndmask_b32_e64 v114, v176, v177, s[0:1]
	v_cndmask_b32_e64 v120, v135, 0, s[22:23]
	s_nop 1
	v_fmac_f32_dpp v169, v115, v120 row_ror:1 row_mask:0xf bank_mask:0xf
	v_and_b32_e32 v115, v114, v204
	v_cndmask_b32_e64 v123, v138, 0, s[20:21]
	v_cndmask_b32_e64 v125, v139, 0, s[20:21]
	s_nop 1
	v_fmac_f32_dpp v166, v171, v123 row_ror:15 row_mask:0xf bank_mask:0xf
	s_nop 1
	v_fmac_f32_dpp v167, v170, v125 row_ror:15 row_mask:0xf bank_mask:0xf
	v_cndmask_b32_e64 v170, v111, v107, s[4:5]
	v_cndmask_b32_e64 v171, v110, v106, s[4:5]
	v_cmp_eq_u32_e64 s[26:27], 0, v115
	v_add_u32_e32 v115, 0x51, v0
	v_cndmask_b32_e64 v119, v138, 0, s[24:25]
	v_cndmask_b32_e64 v121, v139, 0, s[24:25]
	s_nop 1
	v_fmac_f32_dpp v168, v171, v119 row_ror:15 row_mask:0xf bank_mask:0xf
	s_nop 1
	v_fmac_f32_dpp v169, v170, v121 row_ror:15 row_mask:0xf bank_mask:0xf
	v_and_b32_e32 v114, v114, v115
	v_pk_fma_f32 v[170:171], v[106:107], v[130:131], v[142:143]
	v_cndmask_b32_e32 v110, v106, v110, vcc
	v_cmp_gt_i32_e64 s[0:1], s72, v203
	v_pk_fma_f32 v[160:161], v[112:113], v[132:133], v[144:145]
	v_cndmask_b32_e32 v116, v112, v116, vcc
	v_cmp_eq_u32_e64 s[30:31], 0, v114
	v_cndmask_b32_e64 v114, v134, 0, s[26:27]
	v_cndmask_b32_e32 v111, v107, v111, vcc
	s_nop 1
	v_fmac_f32_dpp v170, v110, v114 row_ror:1 row_mask:0xf bank_mask:0xf
	v_cndmask_b32_e64 v110, v176, v177, s[0:1]
	v_cndmask_b32_e64 v122, v136, 0, s[22:23]
	v_cndmask_b32_e64 v124, v137, 0, s[22:23]
	v_cndmask_b32_e64 v125, v141, 0, s[24:25]
	v_cndmask_b32_e32 v117, v113, v117, vcc
	s_nop 1
	v_fmac_f32_dpp v160, v116, v122 row_ror:1 row_mask:0xf bank_mask:0xf
	s_nop 1
	v_fmac_f32_dpp v161, v117, v124 row_ror:1 row_mask:0xf bank_mask:0xf
	v_cndmask_b32_e64 v116, v135, 0, s[26:27]
	s_nop 1
	v_fmac_f32_dpp v171, v111, v116 row_ror:1 row_mask:0xf bank_mask:0xf
	v_and_b32_e32 v111, v110, v203
	v_cndmask_b32_e64 v164, v113, v109, s[4:5]
	s_nop 1
	v_fmac_f32_dpp v161, v164, v125 row_ror:15 row_mask:0xf bank_mask:0xf
	v_cndmask_b32_e64 v124, v107, v103, s[4:5]
	v_cndmask_b32_e64 v125, v106, v102, s[4:5]
	v_cmp_eq_u32_e64 s[36:37], 0, v111
	v_add_u32_e32 v111, 0x61, v0
	v_cndmask_b32_e64 v165, v112, v108, s[4:5]
	v_cndmask_b32_e64 v115, v138, 0, s[30:31]
	v_cndmask_b32_e64 v117, v139, 0, s[30:31]
	s_nop 1
	v_fmac_f32_dpp v170, v125, v115 row_ror:15 row_mask:0xf bank_mask:0xf
	s_nop 1
	v_fmac_f32_dpp v171, v124, v117 row_ror:15 row_mask:0xf bank_mask:0xf
	v_and_b32_e32 v110, v110, v111
	v_pk_fma_f32 v[124:125], v[102:103], v[130:131], v[142:143]
	v_cndmask_b32_e32 v106, v102, v106, vcc
	v_cmp_gt_i32_e64 s[0:1], s72, v190
	v_cndmask_b32_e64 v123, v140, 0, s[24:25]
	s_nop 1
	v_fmac_f32_dpp v160, v165, v123 row_ror:15 row_mask:0xf bank_mask:0xf
	v_pk_fma_f32 v[164:165], v[108:109], v[132:133], v[144:145]
	v_cndmask_b32_e32 v112, v108, v112, vcc
	v_cmp_eq_u32_e64 s[38:39], 0, v110
	v_cndmask_b32_e64 v110, v134, 0, s[36:37]
	v_cndmask_b32_e32 v107, v103, v107, vcc
	s_nop 1
	v_fmac_f32_dpp v124, v106, v110 row_ror:1 row_mask:0xf bank_mask:0xf
	v_cndmask_b32_e64 v106, v176, v177, s[0:1]
	v_cndmask_b32_e64 v118, v136, 0, s[26:27]
	v_cndmask_b32_e64 v120, v137, 0, s[26:27]
	v_cndmask_b32_e64 v121, v141, 0, s[30:31]
	v_cndmask_b32_e32 v113, v109, v113, vcc
	v_cndmask_b32_e64 v122, v109, v105, s[4:5]
	v_cndmask_b32_e64 v123, v108, v104, s[4:5]
	s_nop 1
	v_fmac_f32_dpp v164, v112, v118 row_ror:1 row_mask:0xf bank_mask:0xf
	s_nop 1
	v_fmac_f32_dpp v165, v113, v120 row_ror:1 row_mask:0xf bank_mask:0xf
	v_cndmask_b32_e64 v112, v135, 0, s[36:37]
	s_nop 1
	v_fmac_f32_dpp v125, v107, v112 row_ror:1 row_mask:0xf bank_mask:0xf
	v_and_b32_e32 v107, v106, v190
	v_cndmask_b32_e64 v119, v140, 0, s[30:31]
	s_nop 1
	v_fmac_f32_dpp v164, v123, v119 row_ror:15 row_mask:0xf bank_mask:0xf
	s_nop 1
	v_fmac_f32_dpp v165, v122, v121 row_ror:15 row_mask:0xf bank_mask:0xf
	v_cndmask_b32_e64 v116, v137, 0, s[36:37]
	v_pk_fma_f32 v[122:123], v[104:105], v[132:133], v[144:145]
	v_cndmask_b32_e64 v120, v103, v99, s[4:5]
	v_cndmask_b32_e64 v121, v102, v98, s[4:5]
	v_cmp_eq_u32_e64 s[28:29], 0, v107
	v_add_u32_e32 v107, 0x71, v0
	v_cndmask_b32_e64 v111, v138, 0, s[38:39]
	v_cndmask_b32_e64 v113, v139, 0, s[38:39]
	v_cndmask_b32_e64 v117, v141, 0, s[38:39]
	v_cndmask_b32_e32 v109, v105, v109, vcc
	s_nop 1
	v_fmac_f32_dpp v124, v121, v111 row_ror:15 row_mask:0xf bank_mask:0xf
	s_nop 1
	v_fmac_f32_dpp v125, v120, v113 row_ror:15 row_mask:0xf bank_mask:0xf
	s_nop 1
	v_fmac_f32_dpp v123, v109, v116 row_ror:1 row_mask:0xf bank_mask:0xf
	v_and_b32_e32 v106, v106, v107
	v_pk_fma_f32 v[120:121], v[98:99], v[130:131], v[142:143]
	v_add_co_u32_e64 v116, s[0:1], s33, v150
	v_cndmask_b32_e32 v108, v104, v108, vcc
	v_cndmask_b32_e64 v118, v105, v101, s[4:5]
	s_nop 1
	v_fmac_f32_dpp v123, v118, v117 row_ror:15 row_mask:0xf bank_mask:0xf
	v_cmp_eq_u32_e64 s[34:35], 0, v106
	v_cndmask_b32_e64 v106, v134, 0, s[28:29]
	v_cndmask_b32_e32 v102, v98, v102, vcc
	s_nop 1
	v_fmac_f32_dpp v120, v102, v106 row_ror:1 row_mask:0xf bank_mask:0xf
	v_addc_co_u32_e64 v117, s[0:1], 0, v151, s[0:1]
	v_cndmask_b32_e64 v114, v136, 0, s[36:37]
;     DI void operator()(AccRef acc, const Unit& u, int wr, int wc, int fr, int fq) const {
;     ...
;                     for (int m = 0; m < 4; ++m) {
;                         const int tok = tok0 + 16 * m + fr; const int msk = tok < ML ? 4095 : 255;
;                         const bool hu = (tok & msk) != 0, hd = ((tok + 1) & msk) != 0;
;                         f32x4 r = acc[ai][bj][m][n] * w1 + wb;
;                         f32x4 w0m, w2m;
; #pragma unroll
;                         for (int j = 0; j < 4; ++j) { w0m[j] = hu ? w0[j] : 0.f; w2m[j] = hd ? w2[j] : 0.f; }
; #pragma unroll
;                         for (int j = 0; j < 4; ++j) {
;                             const float su = ((m > 0 || ai == 1) && fr == 15) ? (m > 0 ? acc[ai][bj][(m + 3) & 3][n][j] : acc[0][bj][3][n][j]) : acc[ai][bj][m][n][j];
;                             const float sd = ((m < 3 || ai == 0) && fr == 0) ? (m < 3 ? acc[ai][bj][(m + 1) & 3][n][j] : acc[1][bj][0][n][j]) : acc[ai][bj][m][n][j];
;                             float rj = r[j];
;                             asm("s_nop 1\n\tv_fmac_f32_dpp %0, %1, %2 row_ror:1 row_mask:0xf bank_mask:0xf" : "+v"(rj) : "v"(su), "v"(w0m[j]));
;                             asm("s_nop 1\n\tv_fmac_f32_dpp %0, %1, %2 row_ror:15 row_mask:0xf bank_mask:0xf" : "+v"(rj) : "v"(sd), "v"(w2m[j]));
;                             r[j] = rj; }
	s_nop 1
	v_fmac_f32_dpp v122, v108, v114 row_ror:1 row_mask:0xf bank_mask:0xf
	v_cndmask_b32_e64 v107, v138, 0, s[34:35]
	v_cndmask_b32_e64 v108, v135, 0, s[28:29]
	v_cndmask_b32_e32 v103, v99, v103, vcc
	s_nop 1
	v_fmac_f32_dpp v120, v98, v107 row_ror:15 row_mask:0xf bank_mask:0xf
	s_nop 1
	v_fmac_f32_dpp v121, v103, v108 row_ror:1 row_mask:0xf bank_mask:0xf
	v_add_co_u32_e64 v98, s[0:1], s33, v174
	v_cndmask_b32_e64 v109, v139, 0, s[34:35]
	s_nop 1
	v_fmac_f32_dpp v121, v99, v109 row_ror:15 row_mask:0xf bank_mask:0xf
	s_nop 0
	v_addc_co_u32_e64 v99, s[0:1], 0, v175, s[0:1]
	v_add_co_u32_e64 v106, s[0:1], s33, v172
	v_cndmask_b32_e64 v119, v104, v100, s[4:5]
	s_nop 0
	v_addc_co_u32_e64 v107, s[0:1], 0, v173, s[0:1]
	v_cndmask_b32_e64 v115, v140, 0, s[38:39]
	s_nop 1
	v_fmac_f32_dpp v122, v119, v115 row_ror:15 row_mask:0xf bank_mask:0xf
	v_pk_fma_f32 v[118:119], v[100:101], v[132:133], v[144:145]
	v_add_co_u32_e64 v114, s[0:1], s33, v148
	v_cndmask_b32_e64 v110, v136, 0, s[28:29]
	v_cndmask_b32_e64 v111, v140, 0, s[34:35]
	v_cndmask_b32_e64 v112, v137, 0, s[28:29]
	v_cndmask_b32_e64 v113, v141, 0, s[34:35]
	v_cndmask_b32_e32 v105, v101, v105, vcc
	v_cndmask_b32_e32 v104, v100, v104, vcc
	s_nop 1
	v_fmac_f32_dpp v118, v104, v110 row_ror:1 row_mask:0xf bank_mask:0xf
	s_nop 1
	v_fmac_f32_dpp v119, v105, v112 row_ror:1 row_mask:0xf bank_mask:0xf
	v_addc_co_u32_e64 v115, s[0:1], 0, v149, s[0:1]
	s_nop 1
	v_fmac_f32_dpp v118, v100, v111 row_ror:15 row_mask:0xf bank_mask:0xf
	s_nop 1
	v_fmac_f32_dpp v119, v101, v113 row_ror:15 row_mask:0xf bank_mask:0xf
	v_cndmask_b32_e64 v142, v97, v93, s[4:5]
	v_cndmask_b32_e64 v143, v96, v92, s[4:5]
	v_cndmask_b32_e64 v144, v95, v91, s[4:5]
	v_cndmask_b32_e64 v145, v94, v90, s[4:5]
	v_cndmask_b32_e64 v172, v93, v89, s[4:5]
	v_cndmask_b32_e64 v173, v92, v88, s[4:5]
	v_cndmask_b32_e64 v174, v91, v87, s[4:5]
	v_cndmask_b32_e64 v175, v90, v86, s[4:5]
	v_cmp_gt_u32_e64 s[0:1], s46, v206
	v_cmp_gt_i32_e64 s[42:43], s44, v0
	s_and_b64 s[54:55], s[0:1], s[42:43]
	s_waitcnt vmcnt(0)
	v_pk_fma_f32 v[134:135], v[94:95], v[218:219], v[222:223]
	v_cndmask_b32_e64 v130, v226, 0, s[6:7]
	v_cndmask_b32_e64 v132, v227, 0, s[6:7]
	v_cndmask_b32_e64 v131, v230, 0, s[8:9]
	v_cndmask_b32_e64 v133, v231, 0, s[8:9]
	v_pk_fma_f32 v[136:137], v[96:97], v[220:221], v[224:225]
	s_nop 1
	v_fmac_f32_dpp v134, v94, v130 row_ror:1 row_mask:0xf bank_mask:0xf
	s_nop 1
	v_fmac_f32_dpp v135, v95, v132 row_ror:1 row_mask:0xf bank_mask:0xf
	v_cndmask_b32_e64 v138, v228, 0, s[6:7]
	v_cndmask_b32_e64 v140, v229, 0, s[6:7]
	s_nop 1
	v_fmac_f32_dpp v134, v145, v131 row_ror:15 row_mask:0xf bank_mask:0xf
	s_nop 1
	v_fmac_f32_dpp v135, v144, v133 row_ror:15 row_mask:0xf bank_mask:0xf
	s_nop 1
	v_fmac_f32_dpp v136, v96, v138 row_ror:1 row_mask:0xf bank_mask:0xf
	s_nop 1
	v_fmac_f32_dpp v137, v97, v140 row_ror:1 row_mask:0xf bank_mask:0xf
	v_pk_fma_f32 v[132:133], v[92:93], v[220:221], v[224:225]
	v_pk_fma_f32 v[130:131], v[90:91], v[218:219], v[222:223]
	v_cndmask_b32_e32 v97, v93, v97, vcc
	v_cndmask_b32_e32 v96, v92, v96, vcc
	v_cndmask_b32_e32 v95, v91, v95, vcc
	v_cndmask_b32_e32 v94, v90, v94, vcc
	v_cndmask_b32_e64 v139, v232, 0, s[8:9]
	v_cndmask_b32_e64 v141, v233, 0, s[8:9]
	s_nop 1
	v_fmac_f32_dpp v137, v142, v141 row_ror:15 row_mask:0xf bank_mask:0xf
	v_cndmask_b32_e64 v138, v226, 0, s[10:11]
	v_cndmask_b32_e64 v140, v227, 0, s[10:11]
	v_cndmask_b32_e64 v142, v228, 0, s[10:11]
	v_cndmask_b32_e64 v144, v229, 0, s[10:11]
	s_nop 1
	v_fmac_f32_dpp v130, v94, v138 row_ror:1 row_mask:0xf bank_mask:0xf
	s_nop 1
	v_fmac_f32_dpp v131, v95, v140 row_ror:1 row_mask:0xf bank_mask:0xf
	s_nop 1
	v_fmac_f32_dpp v132, v96, v142 row_ror:1 row_mask:0xf bank_mask:0xf
	s_nop 1
	v_fmac_f32_dpp v133, v97, v144 row_ror:1 row_mask:0xf bank_mask:0xf
	v_pk_fma_f32 v[96:97], v[88:89], v[220:221], v[224:225]
	v_pk_fma_f32 v[94:95], v[86:87], v[218:219], v[222:223]
	v_cndmask_b32_e32 v93, v89, v93, vcc
	v_cndmask_b32_e32 v92, v88, v92, vcc
	v_cndmask_b32_e32 v91, v87, v91, vcc
	v_cndmask_b32_e32 v90, v86, v90, vcc
	s_nop 1
	v_fmac_f32_dpp v136, v143, v139 row_ror:15 row_mask:0xf bank_mask:0xf
	v_cndmask_b32_e64 v139, v230, 0, s[12:13]
	v_cndmask_b32_e64 v141, v231, 0, s[12:13]
	v_cndmask_b32_e64 v143, v232, 0, s[12:13]
	v_cndmask_b32_e64 v145, v233, 0, s[12:13]
	s_nop 1
	v_fmac_f32_dpp v130, v175, v139 row_ror:15 row_mask:0xf bank_mask:0xf
	s_nop 1
	v_fmac_f32_dpp v131, v174, v141 row_ror:15 row_mask:0xf bank_mask:0xf
	s_nop 1
	v_fmac_f32_dpp v132, v173, v143 row_ror:15 row_mask:0xf bank_mask:0xf
	s_nop 1
	v_fmac_f32_dpp v133, v172, v145 row_ror:15 row_mask:0xf bank_mask:0xf
	v_cndmask_b32_e64 v138, v226, 0, s[14:15]
	v_cndmask_b32_e64 v140, v227, 0, s[14:15]
	v_cndmask_b32_e64 v142, v228, 0, s[14:15]
	v_cndmask_b32_e64 v144, v229, 0, s[14:15]
	v_cndmask_b32_e64 v172, v89, v85, s[4:5]
	v_cndmask_b32_e64 v173, v88, v84, s[4:5]
	v_cndmask_b32_e64 v174, v87, v83, s[4:5]
	v_cndmask_b32_e64 v175, v86, v82, s[4:5]
	s_nop 1
	v_fmac_f32_dpp v94, v90, v138 row_ror:1 row_mask:0xf bank_mask:0xf
	s_nop 1
	v_fmac_f32_dpp v95, v91, v140 row_ror:1 row_mask:0xf bank_mask:0xf
	s_nop 1
	v_fmac_f32_dpp v96, v92, v142 row_ror:1 row_mask:0xf bank_mask:0xf
	s_nop 1
	v_fmac_f32_dpp v97, v93, v144 row_ror:1 row_mask:0xf bank_mask:0xf
	v_pk_fma_f32 v[92:93], v[84:85], v[220:221], v[224:225]
	v_pk_fma_f32 v[90:91], v[82:83], v[218:219], v[222:223]
	v_cndmask_b32_e32 v89, v85, v89, vcc
	v_cndmask_b32_e32 v88, v84, v88, vcc
	v_cndmask_b32_e32 v87, v83, v87, vcc
	v_cndmask_b32_e32 v86, v82, v86, vcc
	v_cndmask_b32_e64 v139, v230, 0, s[16:17]
	v_cndmask_b32_e64 v141, v231, 0, s[16:17]
; DI unsigned pk2(float a, float b) { f32x2 v = {a, b}; bfv2 r = __builtin_convertvector(v, bfv2); return __builtin_bit_cast(unsigned, r); }
;     DI void operator()(AccRef acc, const Unit& u, int wr, int wc, int fr, int fq) const {
;     ...
;                     for (int m = 0; m < 4; ++m) {
;                         const int tok = tok0 + 16 * m + fr; const int msk = tok < ML ? 4095 : 255;
;                         const bool hu = (tok & msk) != 0, hd = ((tok + 1) & msk) != 0;
;                         f32x4 r = acc[ai][bj][m][n] * w1 + wb;
;                         f32x4 w0m, w2m;
; #pragma unroll
;                         for (int j = 0; j < 4; ++j) { w0m[j] = hu ? w0[j] : 0.f; w2m[j] = hd ? w2[j] : 0.f; }
; #pragma unroll
;                         for (int j = 0; j < 4; ++j) {
;                             const float su = ((m > 0 || ai == 1) && fr == 15) ? (m > 0 ? acc[ai][bj][(m + 3) & 3][n][j] : acc[0][bj][3][n][j]) : acc[ai][bj][m][n][j];
;                             const float sd = ((m < 3 || ai == 0) && fr == 0) ? (m < 3 ? acc[ai][bj][(m + 1) & 3][n][j] : acc[1][bj][0][n][j]) : acc[ai][bj][m][n][j];
;                             float rj = r[j];
;                             asm("s_nop 1\n\tv_fmac_f32_dpp %0, %1, %2 row_ror:1 row_mask:0xf bank_mask:0xf" : "+v"(rj) : "v"(su), "v"(w0m[j]));
;                             asm("s_nop 1\n\tv_fmac_f32_dpp %0, %1, %2 row_ror:15 row_mask:0xf bank_mask:0xf" : "+v"(rj) : "v"(sd), "v"(w2m[j]));
;                             r[j] = rj; }
;                         if (bj == 0) {
; #pragma unroll
;                             for (int j = 0; j < 4; ++j) o[ai][m][j] = r[j] * __builtin_amdgcn_rcpf(1.f + __builtin_amdgcn_exp2f(-LOG2E * r[j]));
;                         } else o[ai][m] = o[ai][m] * r;
;                     }
;                 }
;             }
; #pragma unroll
;             for (int ai = 0; ai < 2; ++ai) {
;                 const int tok0 = 252 * u.pm - 1 + 126 * wr + 64 * ai;
; #pragma unroll
;                 for (int m = 0; m < 4; ++m) { const int li = 64 * ai + 16 * m + fr, tok = tok0 + 16 * m + fr;
;                     if (li >= 1 && li <= 126 && tok < Mq) { u32x2 v; v.x = pk2(o[ai][m][0], o[ai][m][1]); v.y = pk2(o[ai][m][2], o[ai][m][3]);
	v_cndmask_b32_e64 v143, v232, 0, s[16:17]
	v_cndmask_b32_e64 v145, v233, 0, s[16:17]
	s_nop 1
	v_fmac_f32_dpp v94, v175, v139 row_ror:15 row_mask:0xf bank_mask:0xf
	s_nop 1
	v_fmac_f32_dpp v95, v174, v141 row_ror:15 row_mask:0xf bank_mask:0xf
	s_nop 1
	v_fmac_f32_dpp v96, v173, v143 row_ror:15 row_mask:0xf bank_mask:0xf
	s_nop 1
	v_fmac_f32_dpp v97, v172, v145 row_ror:15 row_mask:0xf bank_mask:0xf
	v_cndmask_b32_e64 v138, v226, 0, s[18:19]
	v_cndmask_b32_e64 v140, v227, 0, s[18:19]
	v_cndmask_b32_e64 v142, v228, 0, s[18:19]
	v_cndmask_b32_e64 v144, v229, 0, s[18:19]
	v_cndmask_b32_e64 v172, v85, v81, s[4:5]
	v_cndmask_b32_e64 v173, v84, v80, s[4:5]
	v_cndmask_b32_e64 v174, v83, v79, s[4:5]
	v_cndmask_b32_e64 v175, v82, v78, s[4:5]
	s_nop 1
	v_fmac_f32_dpp v90, v86, v138 row_ror:1 row_mask:0xf bank_mask:0xf
	s_nop 1
	v_fmac_f32_dpp v91, v87, v140 row_ror:1 row_mask:0xf bank_mask:0xf
	s_nop 1
	v_fmac_f32_dpp v92, v88, v142 row_ror:1 row_mask:0xf bank_mask:0xf
	s_nop 1
	v_fmac_f32_dpp v93, v89, v144 row_ror:1 row_mask:0xf bank_mask:0xf
	v_pk_fma_f32 v[88:89], v[80:81], v[220:221], v[224:225]
	v_pk_fma_f32 v[86:87], v[78:79], v[218:219], v[222:223]
	v_cndmask_b32_e32 v85, v81, v85, vcc
	v_cndmask_b32_e32 v84, v80, v84, vcc
	v_cndmask_b32_e32 v83, v79, v83, vcc
	v_cndmask_b32_e32 v82, v78, v82, vcc
	v_cndmask_b32_e64 v139, v230, 0, s[20:21]
	v_cndmask_b32_e64 v141, v231, 0, s[20:21]
	v_cndmask_b32_e64 v143, v232, 0, s[20:21]
	v_cndmask_b32_e64 v145, v233, 0, s[20:21]
	s_nop 1
	v_fmac_f32_dpp v90, v175, v139 row_ror:15 row_mask:0xf bank_mask:0xf
	s_nop 1
	v_fmac_f32_dpp v91, v174, v141 row_ror:15 row_mask:0xf bank_mask:0xf
	s_nop 1
	v_fmac_f32_dpp v92, v173, v143 row_ror:15 row_mask:0xf bank_mask:0xf
	s_nop 1
	v_fmac_f32_dpp v93, v172, v145 row_ror:15 row_mask:0xf bank_mask:0xf
	v_cndmask_b32_e64 v138, v226, 0, s[22:23]
	v_cndmask_b32_e64 v140, v227, 0, s[22:23]
	v_cndmask_b32_e64 v142, v228, 0, s[22:23]
	v_cndmask_b32_e64 v144, v229, 0, s[22:23]
	v_cndmask_b32_e64 v172, v81, v77, s[4:5]
	v_cndmask_b32_e64 v173, v80, v76, s[4:5]
	v_cndmask_b32_e64 v174, v79, v75, s[4:5]
	v_cndmask_b32_e64 v175, v78, v74, s[4:5]
	s_nop 1
	v_fmac_f32_dpp v86, v82, v138 row_ror:1 row_mask:0xf bank_mask:0xf
	s_nop 1
	v_fmac_f32_dpp v87, v83, v140 row_ror:1 row_mask:0xf bank_mask:0xf
	s_nop 1
	v_fmac_f32_dpp v88, v84, v142 row_ror:1 row_mask:0xf bank_mask:0xf
	s_nop 1
	v_fmac_f32_dpp v89, v85, v144 row_ror:1 row_mask:0xf bank_mask:0xf
	v_pk_fma_f32 v[84:85], v[76:77], v[220:221], v[224:225]
	v_pk_fma_f32 v[82:83], v[74:75], v[218:219], v[222:223]
	v_cndmask_b32_e32 v81, v77, v81, vcc
	v_cndmask_b32_e32 v80, v76, v80, vcc
	v_cndmask_b32_e32 v79, v75, v79, vcc
	v_cndmask_b32_e32 v78, v74, v78, vcc
	v_cndmask_b32_e64 v139, v230, 0, s[24:25]
	v_cndmask_b32_e64 v141, v231, 0, s[24:25]
	v_cndmask_b32_e64 v143, v232, 0, s[24:25]
	v_cndmask_b32_e64 v145, v233, 0, s[24:25]
	s_nop 1
	v_fmac_f32_dpp v86, v175, v139 row_ror:15 row_mask:0xf bank_mask:0xf
	s_nop 1
	v_fmac_f32_dpp v87, v174, v141 row_ror:15 row_mask:0xf bank_mask:0xf
	s_nop 1
	v_fmac_f32_dpp v88, v173, v143 row_ror:15 row_mask:0xf bank_mask:0xf
	s_nop 1
	v_fmac_f32_dpp v89, v172, v145 row_ror:15 row_mask:0xf bank_mask:0xf
	v_cndmask_b32_e64 v138, v226, 0, s[26:27]
	v_cndmask_b32_e64 v140, v227, 0, s[26:27]
	v_cndmask_b32_e64 v142, v228, 0, s[26:27]
	v_cndmask_b32_e64 v144, v229, 0, s[26:27]
	v_cndmask_b32_e64 v172, v77, v73, s[4:5]
	v_cndmask_b32_e64 v173, v76, v72, s[4:5]
	v_cndmask_b32_e64 v174, v75, v71, s[4:5]
	v_cndmask_b32_e64 v175, v74, v70, s[4:5]
	s_nop 1
	v_fmac_f32_dpp v82, v78, v138 row_ror:1 row_mask:0xf bank_mask:0xf
	s_nop 1
	v_fmac_f32_dpp v83, v79, v140 row_ror:1 row_mask:0xf bank_mask:0xf
	s_nop 1
	v_fmac_f32_dpp v84, v80, v142 row_ror:1 row_mask:0xf bank_mask:0xf
	s_nop 1
	v_fmac_f32_dpp v85, v81, v144 row_ror:1 row_mask:0xf bank_mask:0xf
	v_pk_fma_f32 v[80:81], v[72:73], v[220:221], v[224:225]
	v_pk_fma_f32 v[78:79], v[70:71], v[218:219], v[222:223]
	v_cndmask_b32_e32 v77, v73, v77, vcc
	v_cndmask_b32_e32 v76, v72, v76, vcc
	v_cndmask_b32_e32 v75, v71, v75, vcc
	v_cndmask_b32_e32 v74, v70, v74, vcc
	v_cndmask_b32_e64 v138, v226, 0, s[36:37]
	v_cndmask_b32_e64 v140, v227, 0, s[36:37]
	v_cndmask_b32_e64 v142, v228, 0, s[36:37]
	v_cndmask_b32_e64 v144, v229, 0, s[36:37]
	s_nop 1
	v_fmac_f32_dpp v78, v74, v138 row_ror:1 row_mask:0xf bank_mask:0xf
	s_nop 1
	v_fmac_f32_dpp v79, v75, v140 row_ror:1 row_mask:0xf bank_mask:0xf
	s_nop 1
	v_fmac_f32_dpp v80, v76, v142 row_ror:1 row_mask:0xf bank_mask:0xf
	s_nop 1
	v_fmac_f32_dpp v81, v77, v144 row_ror:1 row_mask:0xf bank_mask:0xf
	v_pk_fma_f32 v[76:77], v[68:69], v[220:221], v[224:225]
	v_pk_fma_f32 v[74:75], v[66:67], v[218:219], v[222:223]
	v_cndmask_b32_e64 v139, v230, 0, s[30:31]
	v_cndmask_b32_e64 v141, v231, 0, s[30:31]
	v_cndmask_b32_e64 v143, v232, 0, s[30:31]
	v_cndmask_b32_e64 v145, v233, 0, s[30:31]
	s_nop 1
	v_fmac_f32_dpp v82, v175, v139 row_ror:15 row_mask:0xf bank_mask:0xf
	s_nop 1
	v_fmac_f32_dpp v83, v174, v141 row_ror:15 row_mask:0xf bank_mask:0xf
	s_nop 1
	v_fmac_f32_dpp v84, v173, v143 row_ror:15 row_mask:0xf bank_mask:0xf
	s_nop 1
	v_fmac_f32_dpp v85, v172, v145 row_ror:15 row_mask:0xf bank_mask:0xf
	v_cndmask_b32_e64 v172, v73, v69, s[4:5]
	v_cndmask_b32_e64 v173, v72, v68, s[4:5]
	v_cndmask_b32_e64 v174, v71, v67, s[4:5]
	v_cndmask_b32_e64 v175, v70, v66, s[4:5]
	v_cndmask_b32_e64 v102, v226, 0, s[28:29]
	v_cndmask_b32_e64 v103, v227, 0, s[28:29]
	v_cndmask_b32_e64 v104, v228, 0, s[28:29]
	v_cndmask_b32_e64 v105, v229, 0, s[28:29]
	v_cndmask_b32_e32 v73, v69, v73, vcc
	v_cndmask_b32_e32 v72, v68, v72, vcc
	v_cndmask_b32_e32 v71, v67, v71, vcc
	v_cndmask_b32_e32 v70, v66, v70, vcc
	s_nop 1
	v_fmac_f32_dpp v74, v70, v102 row_ror:1 row_mask:0xf bank_mask:0xf
	s_nop 1
	v_fmac_f32_dpp v75, v71, v103 row_ror:1 row_mask:0xf bank_mask:0xf
	s_nop 1
	v_fmac_f32_dpp v76, v72, v104 row_ror:1 row_mask:0xf bank_mask:0xf
	s_nop 1
	v_fmac_f32_dpp v77, v73, v105 row_ror:1 row_mask:0xf bank_mask:0xf
	v_cndmask_b32_e64 v139, v230, 0, s[38:39]
	v_cndmask_b32_e64 v141, v231, 0, s[38:39]
	v_cndmask_b32_e64 v143, v232, 0, s[38:39]
	v_cndmask_b32_e64 v145, v233, 0, s[38:39]
	s_nop 1
	v_fmac_f32_dpp v78, v175, v139 row_ror:15 row_mask:0xf bank_mask:0xf
	s_nop 1
	v_fmac_f32_dpp v79, v174, v141 row_ror:15 row_mask:0xf bank_mask:0xf
	s_nop 1
	v_fmac_f32_dpp v80, v173, v143 row_ror:15 row_mask:0xf bank_mask:0xf
	s_nop 1
	v_fmac_f32_dpp v81, v172, v145 row_ror:15 row_mask:0xf bank_mask:0xf
	v_cndmask_b32_e64 v106, v230, 0, s[34:35]
	v_cndmask_b32_e64 v107, v231, 0, s[34:35]
	v_cndmask_b32_e64 v108, v232, 0, s[34:35]
	v_cndmask_b32_e64 v109, v233, 0, s[34:35]
	s_nop 1
	v_fmac_f32_dpp v74, v66, v106 row_ror:15 row_mask:0xf bank_mask:0xf
	s_nop 1
	v_fmac_f32_dpp v75, v67, v107 row_ror:15 row_mask:0xf bank_mask:0xf
	s_nop 1
	v_fmac_f32_dpp v76, v68, v108 row_ror:15 row_mask:0xf bank_mask:0xf
	s_nop 1
	v_fmac_f32_dpp v77, v69, v109 row_ror:15 row_mask:0xf bank_mask:0xf
	s_and_saveexec_b64 s[0:1], s[54:55]
	s_cbranch_execz .LBB0_1604
; DI unsigned pk2(float a, float b) { f32x2 v = {a, b}; bfv2 r = __builtin_convertvector(v, bfv2); return __builtin_bit_cast(unsigned, r); }
;     DI void operator()(AccRef acc, const Unit& u, int wr, int wc, int fr, int fq) const {
;     ...
;                             for (int j = 0; j < 4; ++j) o[ai][m][j] = r[j] * __builtin_amdgcn_rcpf(1.f + __builtin_amdgcn_exp2f(-LOG2E * r[j]));
;                         } else o[ai][m] = o[ai][m] * r;
;                     }
;                 }
;             }
; #pragma unroll
;             for (int ai = 0; ai < 2; ++ai) {
;                 const int tok0 = 252 * u.pm - 1 + 126 * wr + 64 * ai;
; #pragma unroll
;                 for (int m = 0; m < 4; ++m) { const int li = 64 * ai + 16 * m + fr, tok = tok0 + 16 * m + fr;
;                     if (li >= 1 && li <= 126 && tok < Mq) { u32x2 v; v.x = pk2(o[ai][m][0], o[ai][m][1]); v.y = pk2(o[ai][m][2], o[ai][m][3]);
;                         *(u32x2*)(ACT + (size_t)tok * DFF + cg_) = v; } }
	v_mul_f32_e32 v66, 0xbfb8aa3b, v154
	v_mul_f32_e32 v67, 0xbfb8aa3b, v155
	v_mul_f32_e32 v68, 0xbfb8aa3b, v152
	v_mul_f32_e32 v69, 0xbfb8aa3b, v153
	v_exp_f32_e32 v66, v66
	v_exp_f32_e32 v67, v67
	v_exp_f32_e32 v68, v68
	v_exp_f32_e32 v69, v69
	v_add_f32_e32 v66, 1.0, v66
	v_add_f32_e32 v67, 1.0, v67
	v_add_f32_e32 v68, 1.0, v68
	v_add_f32_e32 v69, 1.0, v69
	v_rcp_f32_e32 v66, v66
	v_rcp_f32_e32 v67, v67
	v_rcp_f32_e32 v68, v68
	v_rcp_f32_e32 v69, v69
	s_movk_i32 s33, 0x2c00
	v_pk_mul_f32 v[66:67], v[154:155], v[66:67]
	v_pk_mul_f32 v[68:69], v[152:153], v[68:69]
	s_nop 0
	v_pk_mul_f32 v[68:69], v[68:69], v[136:137]
	v_pk_mul_f32 v[66:67], v[66:67], v[134:135]
	s_nop 0
	v_cvt_pk_bf16_f32 v66, v66, v67
	v_cvt_pk_bf16_f32 v67, v68, v69
	v_mov_b64_e32 v[68:69], s[92:93]
	v_mad_i64_i32 v[68:69], s[42:43], v0, s33, v[68:69]
	v_lshl_add_u64 v[68:69], v[146:147], 1, v[68:69]
	global_store_dwordx2 v[68:69], v[66:67], off

; template <class Epi, class SchedT>
; DI void gemm_phase(LAS unsigned char* lds, const Gemm g, const SchedT& S, const Epi& E) {
;     ...
;     auto mk_voff = [&]() { int t2 = threadIdx.x; asm volatile("" : "+v"(t2));
; #pragma unroll
;         for (int i = 0; i < 2; ++i) { int R, C; stage_rc(t2 * 16 + i * 8192, R, C); const int Rb = Epi::PERM ? ((R & ~31) + perm32(R & 31)) : R;
;             const int Ra = g.conv ? ((R >> 6) * 126 + (R & 63)) : R;
;             voffA[i] = (unsigned)(Ra * g.lda + C) * 2u; voffB[i] = (unsigned)(Rb * g.ldb + C) * 2u; } };
;     ...
;         if (has_next) mk_voff();
;         if (!has_next) break;
; #pragma unroll
;         for (int a = 0; a < 2; ++a)
; #pragma unroll
;             for (int b = 0; b < 2; ++b)
; #pragma unroll
;                 for (int m = 0; m < 4; ++m)
; #pragma unroll
;                     for (int n = 0; n < 2; ++n) acc[a][b][m][n] = (f32x4){0.f, 0.f, 0.f, 0.f};
;         cur = nxt; cA = nA; cB = nB; ++ui;
.Lq8_epi_end:
	s_and_b32 s8, s32, 15
	s_cmp_eq_u32 s8, 0
	s_cbranch_scc1 .Lq8_al1
	s_cmp_eq_u32 s65, 1
	s_cbranch_scc0 .Lq8_al1
	s_barrier
.Lq8_al1:
	s_mov_b64 s[0:1], -1
	s_and_b64 vcc, exec, s[2:3]
	s_cbranch_vccz .LBB0_1595
	v_mov_b32_e32 v0, v192
	s_mov_b32 s2, 0xfffe0
	v_ashrrev_i32_e32 v2, 31, v0
	v_lshrrev_b32_e32 v2, 26, v2
	v_lshlrev_b32_e32 v4, 4, v0
	v_add_u32_e32 v2, v0, v2
	v_bfe_i32 v0, v0, 27, 1
	v_lshrrev_b32_e32 v0, 22, v0
	v_add_u32_e32 v0, v4, v0
	v_and_b32_e32 v0, 0xfffffc00, v0
	v_sub_u32_e32 v0, v4, v0
	v_lshrrev_b32_e32 v3, 4, v0
	v_bitop3_b32 v0, v3, v0, 32 bitop3:0x6c
	v_ashrrev_i32_e32 v5, 31, v0
	v_ashrrev_i32_e32 v2, 6, v2
	v_lshrrev_b32_e32 v5, 26, v5
	v_lshlrev_b32_e32 v3, 3, v2
	v_add_u32_e32 v5, v0, v5
	v_lshlrev_b32_e32 v2, 5, v2
	v_and_b32_e32 v7, 32, v2
	v_and_b32_e32 v2, 0xc0, v5
	v_and_b32_e32 v3, -16, v3
	v_ashrrev_i32_e32 v6, 6, v5
	v_sub_u32_e32 v0, v0, v2
	v_add_u32_e32 v3, v6, v3
	v_ashrrev_i16_sdwa v0, v200, sext(v0) dst_sel:DWORD dst_unused:UNUSED_PAD src0_sel:DWORD src1_sel:BYTE_0
	v_bfe_i32 v5, v0, 0, 16
	v_lshlrev_b32_e32 v0, 1, v3
	v_lshrrev_b32_e32 v2, 2, v3
	v_and_b32_e32 v6, 3, v6
	v_and_b32_e32 v0, 24, v0
	v_and_b32_e32 v2, 4, v2
	v_and_or_b32 v6, v3, s2, v6
	v_or3_b32 v6, v6, v2, v0
	v_lshrrev_b32_e32 v2, 6, v3
	v_and_b32_e32 v0, 63, v3
	v_mad_u64_u32 v[2:3], s[0:1], v2, s46, v[0:1]
	v_add_lshl_u32 v3, v7, v5, 1
	v_lshl_add_u32 v0, v2, 12, v3
	v_add_u32_e32 v2, 0x2000, v4
	v_lshl_add_u32 v130, v6, 12, v3
	v_ashrrev_i32_e32 v3, 31, v2
	v_lshrrev_b32_e32 v3, 22, v3
	v_add_u32_e32 v3, v2, v3
	v_ashrrev_i32_e32 v3, 10, v3
	v_mul_i32_i24_e32 v4, 0x400, v3
	v_sub_u32_e32 v2, v2, v4
	v_lshrrev_b32_e32 v4, 4, v2
	v_bitop3_b32 v2, v4, v2, 32 bitop3:0x6c
	v_ashrrev_i32_e32 v5, 31, v2
	v_lshrrev_b32_e32 v5, 26, v5
	v_lshlrev_b32_e32 v4, 3, v3
	v_add_u32_e32 v5, v2, v5
	v_lshlrev_b32_e32 v3, 5, v3
	v_and_b32_e32 v7, 32, v3
	v_and_b32_e32 v3, 0xc0, v5
	v_and_b32_e32 v4, -16, v4
	v_ashrrev_i32_e32 v6, 6, v5
	v_sub_u32_e32 v2, v2, v3
	v_add_u32_e32 v4, v6, v4
	v_ashrrev_i16_sdwa v2, v200, sext(v2) dst_sel:DWORD dst_unused:UNUSED_PAD src0_sel:DWORD src1_sel:BYTE_0
	v_bfe_i32 v5, v2, 0, 16
	v_lshlrev_b32_e32 v2, 1, v4
	v_lshrrev_b32_e32 v3, 2, v4
	v_and_b32_e32 v6, 3, v6
	v_and_b32_e32 v2, 24, v2
	v_and_b32_e32 v3, 4, v3
	v_and_or_b32 v6, v4, s2, v6
	v_or3_b32 v6, v6, v3, v2
	v_lshrrev_b32_e32 v3, 6, v4
	v_and_b32_e32 v2, 63, v4
	v_mad_u64_u32 v[2:3], s[0:1], v3, s46, v[2:3]
	v_add_lshl_u32 v3, v7, v5, 1
	v_lshl_add_u32 v132, v2, 12, v3
	v_lshl_add_u32 v134, v6, 12, v3
	s_mov_b64 s[0:1], 0
	s_branch .LBB0_1595
